# grid barrier: non-last workgroups of an XCD invalidate L1 right after arriving instead of after the release (no shared-data loads happen in between); plus earlier edits (hand-written in-proj epilogue,
# speedup vs baseline: 1.0258x; 1.0165x over previous
; __device__ __forceinline__ unsigned xb_ld(unsigned* p)              { return __hip_atomic_load((GAS unsigned*)p, __ATOMIC_RELAXED, __HIP_MEMORY_SCOPE_AGENT); }
; __device__ __forceinline__ unsigned xb_add(unsigned* p, unsigned v) { return __hip_atomic_fetch_add((GAS unsigned*)p, v, __ATOMIC_RELAXED, __HIP_MEMORY_SCOPE_AGENT); }
; #define XB_SPIN(cond, bar) do { unsigned _sp = 0; while (cond) { __builtin_amdgcn_s_sleep(1); \
;     if ((++_sp & 255u) == 0u) { if (xb_ld(&(bar)[XB_TMO])) break; if (_sp > XB_SPIN_CAP) { atomicAdd(&(bar)[XB_TMO], 1u); break; } } } } while (0)
; __device__ __forceinline__ void xcd_barrier(const XcdBarrier& b) {
;     ...
;         const unsigned old = xb_add(&bar[XB_XSUB(bx)], 1u);
;         const unsigned gen = old / nloc;
;         if (old + 1u == (gen + 1u) * nloc) {
;             __builtin_amdgcn_fence(__ATOMIC_RELEASE, "agent");
;             asm volatile("s_waitcnt vmcnt(0)" ::: "memory");
;             const unsigned og = xb_add(&bar[XB_TOP], 1u);
;             const unsigned tg = og / nx;
;             if (og + 1u == (tg + 1u) * nx) xb_add(&bar[XB_TOPGEN], 1u);
;             else XB_SPIN(xb_ld(&bar[XB_TOPGEN]) == tg, bar);
;             __builtin_amdgcn_fence(__ATOMIC_ACQUIRE, "agent");
;             xb_add(&bar[XB_XGEN(bx)], 1u);
;             asm volatile("s_waitcnt vmcnt(0)" ::: "memory");
;         } else {
;             XB_SPIN(xb_ld(&bar[XB_XGEN(bx)]) == gen, bar);
;             __builtin_amdgcn_fence(__ATOMIC_ACQUIRE, "agent");
.LBB0_196:
	s_or_b64 exec, exec, s[10:11]
	v_cvt_f32_u32_e32 v4, v2
	s_waitcnt vmcnt(0)
	v_readfirstlane_b32 s8, v3
	v_sub_u32_e32 v3, 0, v2
	v_rcp_iflag_f32_e32 v4, v4
	v_add_u32_e32 v5, s8, v1
	v_mul_f32_e32 v4, 0x4f7ffffe, v4
	v_cvt_u32_f32_e32 v4, v4
	v_mul_lo_u32 v1, v3, v4
	v_mul_hi_u32 v1, v4, v1
	v_add_u32_e32 v1, v4, v1
	v_mul_hi_u32 v1, v5, v1
	v_mul_lo_u32 v3, v1, v2
	v_sub_u32_e32 v3, v5, v3
	v_add_u32_e32 v4, 1, v1
	v_cmp_ge_u32_e32 vcc, v3, v2
	s_nop 1
	v_cndmask_b32_e32 v1, v1, v4, vcc
	v_sub_u32_e32 v4, v3, v2
	v_cndmask_b32_e32 v3, v3, v4, vcc
	v_add_u32_e32 v4, 1, v1
	v_cmp_ge_u32_e32 vcc, v3, v2
	v_add_u32_e32 v3, 1, v5
	s_nop 0
	v_cndmask_b32_e32 v1, v1, v4, vcc
	v_mul_lo_u32 v4, v2, v1
	v_add_u32_e32 v2, v4, v2
	v_cmp_ne_u32_e32 vcc, v3, v2
	s_and_saveexec_b64 s[8:9], vcc
	s_xor_b64 s[8:9], exec, s[8:9]
	s_cbranch_execz .LBB0_209
	buffer_inv sc1
	s_add_i32 s10, s3, 0x900
	s_mov_b32 s11, 0
	s_lshl_b64 s[10:11], s[10:11], 2
	s_add_u32 s12, s6, s10
	s_addc_u32 s13, s7, s11
	s_waitcnt lgkmcnt(0)
	v_mov_b32_e32 v0, 0
	global_load_dword v2, v0, s[12:13] sc1
	s_waitcnt vmcnt(0)
	v_cmp_eq_u32_e32 vcc, v2, v1
	s_and_saveexec_b64 s[10:11], vcc
	s_cbranch_execz .LBB0_208
	s_mov_b32 s26, 1
	s_mov_b64 s[14:15], 0
	s_branch .LBB0_200

; __device__ __forceinline__ unsigned xb_ld(unsigned* p)              { return __hip_atomic_load((GAS unsigned*)p, __ATOMIC_RELAXED, __HIP_MEMORY_SCOPE_AGENT); }
; #define XB_SPIN(cond, bar) do { unsigned _sp = 0; while (cond) { __builtin_amdgcn_s_sleep(1); \
;     if ((++_sp & 255u) == 0u) { if (xb_ld(&(bar)[XB_TMO])) break; if (_sp > XB_SPIN_CAP) { atomicAdd(&(bar)[XB_TMO], 1u); break; } } } } while (0)
; __device__ __forceinline__ void xcd_barrier(const XcdBarrier& b) {
;     ...
;             XB_SPIN(xb_ld(&bar[XB_XGEN(bx)]) == gen, bar);
;             __builtin_amdgcn_fence(__ATOMIC_ACQUIRE, "agent");
;             asm volatile("s_waitcnt vmcnt(0)" ::: "memory");
.LBB0_208:
	s_or_b64 exec, exec, s[10:11]
	s_waitcnt vmcnt(0) lgkmcnt(0)
	s_nop 0
	s_waitcnt vmcnt(0)

;     __device__ __forceinline__ void operator()(const f32x4 (&acc)[2][2][4][2], const pg8::Unit& u, int wr, int wc, int fr_, int fq_) const {
;     ...
;         const bool rope = pn < 2 || (pn == 2 && wc < 2);
;         const int row0 = u.pm * 256 + wr * 64 + fr, cw = wc * 32 + fq * 8;
;         Ld ld[8];
; #pragma unroll
;         for (int it = 0; it < 10; ++it) {
;             if (it < 8) {
;                 const int row = row0 + (it >> 2) * 128 + (it & 3) * 16;
;                 ld[it].ss = gld<f32x4>(ssp + (size_t)row * 16 + fq * 4);
;                 if (rope) { const int pidx = row < NPR ? (row & 2047) : 2048 + (row & 3); const float* tp = tab + (size_t)pidx * 64 + fq * 8;
;                     ld[it].c0 = gld<f32x4>(tp); ld[it].c1 = gld<f32x4>(tp + 4); ld[it].s0 = gld<f32x4>(tp + 32); ld[it].s1 = gld<f32x4>(tp + 36); }
.LBB0_280:
	s_cmp_lg_u32 s6, 2
	s_cbranch_scc1 .Lme_entry
	s_cmp_gt_i32 s6, 1
	v_mov_b32_e32 v190, v248
	s_mov_b64 s[8:9], s[0:1]
	s_cselect_b64 s[16:17], -1, 0
	s_cmp_lt_i32 s6, 2
	s_cselect_b64 s[18:19], -1, 0
	s_cmp_lg_u32 s6, 2
	s_load_dwordx2 s[10:11], s[8:9], 0x80
	s_cselect_b64 s[8:9], -1, 0
	s_cmp_eq_u32 s6, 2
	s_cselect_b64 s[30:31], -1, 0
	s_lshl_b32 s71, s4, 8
	v_ashrrev_i32_e32 v98, 4, v190
	s_add_i32 s71, s71, s89
	v_and_or_b32 v210, v190, 15, s71
	v_lshlrev_b32_e32 v96, 2, v98
	v_ashrrev_i32_e32 v97, 31, v96
	v_ashrrev_i32_e32 v211, 31, v210
	s_waitcnt lgkmcnt(0)
	v_lshl_add_u64 v[236:237], v[96:97], 2, s[10:11]
	v_lshlrev_b64 v[96:97], 6, v[210:211]
	s_mov_b64 s[12:13], s[0:1]
	v_lshl_add_u64 v[96:97], v[236:237], 0, v[96:97]
	global_load_dwordx4 v[184:187], v[96:97], off
	s_load_dwordx2 s[28:29], s[12:13], 0x78
	s_and_b64 s[4:5], s[30:31], s[66:67]
	v_lshlrev_b32_e32 v188, 3, v98
	s_or_b64 s[4:5], s[18:19], s[4:5]
	v_ashrrev_i32_e32 v189, 31, v188
	s_xor_b64 s[84:85], s[4:5], -1
	v_and_b32_e32 v191, 3, v190
	v_lshl_add_u64 v[96:97], v[188:189], 2, s[10:11]
	s_mov_b64 s[12:13], 0xfd00000
	v_or_b32_e32 v252, 0x800, v191
	v_lshl_add_u64 v[234:235], v[96:97], 0, s[12:13]
	s_and_b64 vcc, exec, s[84:85]
	s_cbranch_vccnz .LBB0_282
	v_and_b32_e32 v96, 0x7cf, v210
	v_cmp_gt_i32_e32 vcc, s44, v210
	s_nop 1
	v_cndmask_b32_e32 v96, v252, v96, vcc
	v_lshlrev_b32_e32 v192, 8, v96
	v_lshl_add_u64 v[96:97], v[234:235], 0, v[192:193]
	global_load_dwordx4 v[152:155], v[96:97], off offset:16
	global_load_dwordx4 v[176:179], v[96:97], off
	global_load_dwordx4 v[172:175], v[96:97], off offset:144
	global_load_dwordx4 v[180:183], v[96:97], off offset:128

; __device__ __forceinline__ u32x4 pk8(f32x4 a, f32x4 b) { u32x4 w; w.x = pk2(a[0], a[1]); w.y = pk2(a[2], a[3]); w.z = pk2(b[0], b[1]); w.w = pk2(b[2], b[3]); return w; }
;     __device__ __forceinline__ void operator()(const f32x4 (&acc)[2][2][4][2], const pg8::Unit& u, int wr, int wc, int fr_, int fq_) const {
;     ...
;                 const int row = row0 + (it >> 2) * 128 + (it & 3) * 16;
;                 ld[it].ss = gld<f32x4>(ssp + (size_t)row * 16 + fq * 4);
;                 if (rope) { const int pidx = row < NPR ? (row & 2047) : 2048 + (row & 3); const float* tp = tab + (size_t)pidx * 64 + fq * 8;
;                     ld[it].c0 = gld<f32x4>(tp); ld[it].c1 = gld<f32x4>(tp + 4); ld[it].s0 = gld<f32x4>(tp + 32); ld[it].s1 = gld<f32x4>(tp + 36); }
;             }
;             if (it >= 2) {
;                 const int k = it - 2, ai = k >> 2, m = k & 3, row = row0 + ai * 128 + m * 16;
;                 float sq = (ld[k].ss[0] + ld[k].ss[1]) + (ld[k].ss[2] + ld[k].ss[3]); sq += __shfl_xor(sq, 16); sq += __shfl_xor(sq, 32);
;                 const float rs = __builtin_amdgcn_rsqf(sq * (1.f / 1024.f) + EPS);
;                 const f32x4 a0 = acc[ai][0][m][0] * rs, a1 = acc[ai][0][m][1] * rs, b0 = acc[ai][1][m][0] * rs, b1 = acc[ai][1][m][1] * rs;
;                 if (rope) {
;                     const f32x4 c0 = ld[k].c0, c1 = ld[k].c1, s0 = ld[k].s0, s1 = ld[k].s1;
;                     f32x4 o1a = a0 * c0 - b0 * s0, o1b = a1 * c1 - b1 * s1, o2a = b0 * c0 + a0 * s0, o2b = b1 * c1 + a1 * s1;
;                     if (pn < 2) {
;                         o1a *= QS; o1b *= QS; o2a *= QS; o2b *= QS;
;                         bf16_t* q = Q + (size_t)row * 512 + (4 * pn + wc) * 64 + fq * 8;
;                         gst<u32x4>(q, pk8(o1a, o1b)); gst<u32x4>(q + 32, pk8(o2a, o2b));
.Lme_entry:
	s_load_dwordx2 s[10:11], s[0:1], 0x80
	s_load_dwordx2 s[28:29], s[0:1], 0x78
	v_readlane_b32 s20, v255, 36
	s_lshl_b32 s71, s4, 8
	s_add_i32 s71, s71, s89
	v_and_or_b32 v210, v248, 15, s71
	v_lshrrev_b32_e32 v211, 4, v248
	v_lshlrev_b32_e32 v212, 6, v210
	v_lshl_add_u32 v212, v211, 4, v212
	v_add_u32_e32 v213, 0x2000, v212
	v_xor_b32_e32 v250, 16, v248
	v_lshlrev_b32_e32 v250, 2, v250
	v_xor_b32_e32 v251, 32, v248
	v_lshlrev_b32_e32 v251, 2, v251
	v_lshlrev_b32_e32 v214, 10, v210
	v_lshl_add_u32 v214, v211, 4, v214
	s_waitcnt lgkmcnt(0)
	global_load_dwordx4 v[144:147], v212, s[10:11]
	global_load_dwordx4 v[148:151], v212, s[10:11] offset:1024
	global_load_dwordx4 v[152:155], v212, s[10:11] offset:2048
	global_load_dwordx4 v[156:159], v212, s[10:11] offset:3072
	global_load_dwordx4 v[160:163], v213, s[10:11]
	global_load_dwordx4 v[164:167], v213, s[10:11] offset:1024
	global_load_dwordx4 v[168:171], v213, s[10:11] offset:2048
	global_load_dwordx4 v[172:175], v213, s[10:11] offset:3072
	s_cmp_gt_i32 s6, 1
	s_cbranch_scc1 .Lme_notq
	s_and_b32 s5, s4, 7
	s_lshl_b32 s5, s5, 8
	s_add_i32 s5, s5, s89
	v_and_b32_e32 v252, 15, v248
	v_add_u32_e32 v252, s5, v252
	s_mov_b32 s7, 0x1000
	s_mov_b32 s8, 0x5000
	s_cmp_gt_i32 s4, 63
	s_cbranch_scc0 .Lme_qprompt
	v_and_b32_e32 v252, 3, v248
	v_add_u32_e32 v252, 0x800, v252
	s_mov_b32 s7, 0
	s_mov_b32 s8, 0
.Lme_qprompt:
	v_lshlrev_b32_e32 v252, 8, v252
	v_lshl_add_u32 v252, v211, 5, v252
	s_add_u32 s12, s10, 0xfd00000
	s_addc_u32 s13, s11, 0
	global_load_dwordx4 v[96:99], v252, s[12:13]
	global_load_dwordx4 v[100:103], v252, s[12:13] offset:16
	global_load_dwordx4 v[104:107], v252, s[12:13] offset:128
	global_load_dwordx4 v[108:111], v252, s[12:13] offset:144
	v_add_u32_e32 v252, s7, v252
	global_load_dwordx4 v[218:221], v252, s[12:13]
	global_load_dwordx4 v[222:225], v252, s[12:13] offset:16
	global_load_dwordx4 v[226:229], v252, s[12:13] offset:128
	global_load_dwordx4 v[230:233], v252, s[12:13] offset:144
	v_add_u32_e32 v252, s7, v252
	s_lshl_b32 s5, s6, 9
	s_lshl_b32 s9, s93, 1
	s_add_i32 s5, s5, s9
	s_add_u32 s5, s5, 0xb200000
	s_add_u32 s16, s10, s5
	s_addc_u32 s17, s11, 0
	s_mov_b32 s30, s48
	s_mov_b32 s31, s48
	s_waitcnt vmcnt(8)
	s_branch .Lme_reduce
.Lme_notq:
	s_cmp_gt_i32 s6, 8
	s_cbranch_scc1 .Lme_ubase
	s_cmp_gt_i32 s6, 4
	s_cbranch_scc1 .Lme_bbase
	s_add_i32 s12, s6, -3
	s_lshl_b32 s12, s12, 9
	s_add_i32 s12, s12, s93
	s_add_u32 s12, s12, 0xc280000
	s_branch .Lme_base_done

; __device__ __forceinline__ u32x4 pk8(f32x4 a, f32x4 b) { u32x4 w; w.x = pk2(a[0], a[1]); w.y = pk2(a[2], a[3]); w.z = pk2(b[0], b[1]); w.w = pk2(b[2], b[3]); return w; }
;     __device__ __forceinline__ void operator()(const f32x4 (&acc)[2][2][4][2], const pg8::Unit& u, int wr, int wc, int fr_, int fq_) const {
;     ...
;                 float sq = (ld[k].ss[0] + ld[k].ss[1]) + (ld[k].ss[2] + ld[k].ss[3]); sq += __shfl_xor(sq, 16); sq += __shfl_xor(sq, 32);
;                 const float rs = __builtin_amdgcn_rsqf(sq * (1.f / 1024.f) + EPS);
;                 const f32x4 a0 = acc[ai][0][m][0] * rs, a1 = acc[ai][0][m][1] * rs, b0 = acc[ai][1][m][0] * rs, b1 = acc[ai][1][m][1] * rs;
;                 if (rope) {
;                     const f32x4 c0 = ld[k].c0, c1 = ld[k].c1, s0 = ld[k].s0, s1 = ld[k].s1;
;                     f32x4 o1a = a0 * c0 - b0 * s0, o1b = a1 * c1 - b1 * s1, o2a = b0 * c0 + a0 * s0, o2b = b1 * c1 + a1 * s1;
;                     if (pn < 2) {
;                         o1a *= QS; o1b *= QS; o2a *= QS; o2b *= QS;
;                         bf16_t* q = Q + (size_t)row * 512 + (4 * pn + wc) * 64 + fq * 8;
;                         gst<u32x4>(q, pk8(o1a, o1b)); gst<u32x4>(q + 32, pk8(o2a, o2b));
.Lme_reduce:
	v_add_f32_e32 v144, v144, v145
	v_add_f32_e32 v146, v146, v147
	v_add_f32_e32 v148, v148, v149
	v_add_f32_e32 v150, v150, v151
	v_add_f32_e32 v152, v152, v153
	v_add_f32_e32 v154, v154, v155
	v_add_f32_e32 v156, v156, v157
	v_add_f32_e32 v158, v158, v159
	v_add_f32_e32 v160, v160, v161
	v_add_f32_e32 v162, v162, v163
	v_add_f32_e32 v164, v164, v165
	v_add_f32_e32 v166, v166, v167
	v_add_f32_e32 v168, v168, v169
	v_add_f32_e32 v170, v170, v171
	v_add_f32_e32 v172, v172, v173
	v_add_f32_e32 v174, v174, v175
	v_add_f32_e32 v144, v144, v146
	v_add_f32_e32 v148, v148, v150
	v_add_f32_e32 v152, v152, v154
	v_add_f32_e32 v156, v156, v158
	v_add_f32_e32 v160, v160, v162
	v_add_f32_e32 v164, v164, v166
	v_add_f32_e32 v168, v168, v170
	v_add_f32_e32 v172, v172, v174
	ds_bpermute_b32 v145, v250, v144
	ds_bpermute_b32 v149, v250, v148
	ds_bpermute_b32 v153, v250, v152
	ds_bpermute_b32 v157, v250, v156
	ds_bpermute_b32 v161, v250, v160
	ds_bpermute_b32 v165, v250, v164
	ds_bpermute_b32 v169, v250, v168
	ds_bpermute_b32 v173, v250, v172
	s_waitcnt lgkmcnt(0)
	v_add_f32_e32 v144, v144, v145
	v_add_f32_e32 v148, v148, v149
	v_add_f32_e32 v152, v152, v153
	v_add_f32_e32 v156, v156, v157
	v_add_f32_e32 v160, v160, v161
	v_add_f32_e32 v164, v164, v165
	v_add_f32_e32 v168, v168, v169
	v_add_f32_e32 v172, v172, v173
	ds_bpermute_b32 v145, v251, v144
	ds_bpermute_b32 v149, v251, v148
	ds_bpermute_b32 v153, v251, v152
	ds_bpermute_b32 v157, v251, v156
	ds_bpermute_b32 v161, v251, v160
	ds_bpermute_b32 v165, v251, v164
	ds_bpermute_b32 v169, v251, v168
	ds_bpermute_b32 v173, v251, v172
	s_waitcnt lgkmcnt(0)
	v_add_f32_e32 v144, v144, v145
	v_add_f32_e32 v148, v148, v149
	v_add_f32_e32 v152, v152, v153
	v_add_f32_e32 v156, v156, v157
	v_add_f32_e32 v160, v160, v161
	v_add_f32_e32 v164, v164, v165
	v_add_f32_e32 v168, v168, v169
	v_add_f32_e32 v172, v172, v173
	v_fmamk_f32 v144, v144, 0x3a800000, v243
	v_fmamk_f32 v148, v148, 0x3a800000, v243
	v_fmamk_f32 v152, v152, 0x3a800000, v243
	v_fmamk_f32 v156, v156, 0x3a800000, v243
	v_fmamk_f32 v160, v160, 0x3a800000, v243
	v_fmamk_f32 v164, v164, 0x3a800000, v243
	v_fmamk_f32 v168, v168, 0x3a800000, v243
	v_fmamk_f32 v172, v172, 0x3a800000, v243
	v_rsq_f32_e32 v176, v144
	v_rsq_f32_e32 v178, v148
	v_rsq_f32_e32 v180, v152
	v_rsq_f32_e32 v182, v156
	v_rsq_f32_e32 v184, v160
	v_rsq_f32_e32 v186, v164
	v_rsq_f32_e32 v188, v168
	v_rsq_f32_e32 v190, v172
	s_cmp_gt_i32 s6, 8
	s_cbranch_scc1 .Lme_upath
	s_cmp_gt_i32 s6, 4
	s_cbranch_scc1 .Lme_bpath
	s_cmp_gt_i32 s6, 2
	s_cbranch_scc1 .Lme_spath
	global_load_dwordx4 v[144:147], v252, s[12:13]
	global_load_dwordx4 v[148:151], v252, s[12:13] offset:16
	global_load_dwordx4 v[152:155], v252, s[12:13] offset:128
	global_load_dwordx4 v[156:159], v252, s[12:13] offset:144
	v_add_u32_e32 v252, s7, v252
	global_load_dwordx4 v[160:163], v252, s[12:13]
	global_load_dwordx4 v[164:167], v252, s[12:13] offset:16
	global_load_dwordx4 v[168:171], v252, s[12:13] offset:128
	global_load_dwordx4 v[172:175], v252, s[12:13] offset:144
	v_add_u32_e32 v252, s8, v252
	v_pk_mul_f32 v[132:133], v[132:133], v[176:177] op_sel_hi:[1,0]
	v_pk_mul_f32 v[134:135], v[134:135], v[176:177] op_sel_hi:[1,0]
	v_pk_mul_f32 v[128:129], v[128:129], v[176:177] op_sel_hi:[1,0]
	v_pk_mul_f32 v[130:131], v[130:131], v[176:177] op_sel_hi:[1,0]
	v_pk_mul_f32 v[116:117], v[116:117], v[176:177] op_sel_hi:[1,0]
	v_pk_mul_f32 v[118:119], v[118:119], v[176:177] op_sel_hi:[1,0]
	v_pk_mul_f32 v[112:113], v[112:113], v[176:177] op_sel_hi:[1,0]
	v_pk_mul_f32 v[114:115], v[114:115], v[176:177] op_sel_hi:[1,0]
	s_waitcnt vmcnt(12)
	v_pk_mul_f32 v[234:235], v[116:117], v[104:105]
	v_pk_mul_f32 v[236:237], v[118:119], v[106:107]
	v_pk_mul_f32 v[238:239], v[112:113], v[108:109]
	v_pk_mul_f32 v[240:241], v[114:115], v[110:111]
	v_pk_fma_f32 v[234:235], v[132:133], v[96:97], v[234:235] neg_lo:[0,0,1] neg_hi:[0,0,1]
	v_pk_fma_f32 v[236:237], v[134:135], v[98:99], v[236:237] neg_lo:[0,0,1] neg_hi:[0,0,1]
	v_pk_fma_f32 v[238:239], v[128:129], v[100:101], v[238:239] neg_lo:[0,0,1] neg_hi:[0,0,1]
	v_pk_fma_f32 v[240:241], v[130:131], v[102:103], v[240:241] neg_lo:[0,0,1] neg_hi:[0,0,1]
	v_pk_mul_f32 v[104:105], v[132:133], v[104:105]
	v_pk_mul_f32 v[106:107], v[134:135], v[106:107]
	v_pk_mul_f32 v[108:109], v[128:129], v[108:109]
	v_pk_mul_f32 v[110:111], v[130:131], v[110:111]
	v_pk_fma_f32 v[104:105], v[116:117], v[96:97], v[104:105]
	v_pk_fma_f32 v[106:107], v[118:119], v[98:99], v[106:107]
	v_pk_fma_f32 v[108:109], v[112:113], v[100:101], v[108:109]
	v_pk_fma_f32 v[110:111], v[114:115], v[102:103], v[110:111]
	v_pk_mul_f32 v[234:235], v[234:235], s[30:31]
	v_pk_mul_f32 v[236:237], v[236:237], s[30:31]
	v_pk_mul_f32 v[238:239], v[238:239], s[30:31]
	v_pk_mul_f32 v[240:241], v[240:241], s[30:31]
	v_pk_mul_f32 v[104:105], v[104:105], s[30:31]
	v_pk_mul_f32 v[106:107], v[106:107], s[30:31]
	v_pk_mul_f32 v[108:109], v[108:109], s[30:31]
	v_pk_mul_f32 v[110:111], v[110:111], s[30:31]
	v_cvt_pk_bf16_f32 v132, v234, v235
	v_cvt_pk_bf16_f32 v133, v236, v237
	v_cvt_pk_bf16_f32 v134, v238, v239
	v_cvt_pk_bf16_f32 v135, v240, v241
	global_store_dwordx4 v214, v[132:135], s[16:17]
	v_cvt_pk_bf16_f32 v116, v104, v105
	v_cvt_pk_bf16_f32 v117, v106, v107
	v_cvt_pk_bf16_f32 v118, v108, v109
	v_cvt_pk_bf16_f32 v119, v110, v111
	global_store_dwordx4 v214, v[116:119], s[16:17] offset:64
	s_add_u32 s16, s16, 0x4000
	s_addc_u32 s17, s17, 0
	global_load_dwordx4 v[96:99], v252, s[12:13]
	global_load_dwordx4 v[100:103], v252, s[12:13] offset:16
	global_load_dwordx4 v[104:107], v252, s[12:13] offset:128
	global_load_dwordx4 v[108:111], v252, s[12:13] offset:144
	v_add_u32_e32 v252, s7, v252
	v_pk_mul_f32 v[140:141], v[140:141], v[178:179] op_sel_hi:[1,0]
	v_pk_mul_f32 v[142:143], v[142:143], v[178:179] op_sel_hi:[1,0]
	v_pk_mul_f32 v[136:137], v[136:137], v[178:179] op_sel_hi:[1,0]
	v_pk_mul_f32 v[138:139], v[138:139], v[178:179] op_sel_hi:[1,0]
	v_pk_mul_f32 v[124:125], v[124:125], v[178:179] op_sel_hi:[1,0]
	v_pk_mul_f32 v[126:127], v[126:127], v[178:179] op_sel_hi:[1,0]
	v_pk_mul_f32 v[120:121], v[120:121], v[178:179] op_sel_hi:[1,0]
	v_pk_mul_f32 v[122:123], v[122:123], v[178:179] op_sel_hi:[1,0]
	s_waitcnt vmcnt(14)
; __device__ __forceinline__ u32x4 pk8(f32x4 a, f32x4 b) { u32x4 w; w.x = pk2(a[0], a[1]); w.y = pk2(a[2], a[3]); w.z = pk2(b[0], b[1]); w.w = pk2(b[2], b[3]); return w; }
;     __device__ __forceinline__ void operator()(const f32x4 (&acc)[2][2][4][2], const pg8::Unit& u, int wr, int wc, int fr_, int fq_) const {
;     ...
;                 const f32x4 a0 = acc[ai][0][m][0] * rs, a1 = acc[ai][0][m][1] * rs, b0 = acc[ai][1][m][0] * rs, b1 = acc[ai][1][m][1] * rs;
;                 if (rope) {
;                     const f32x4 c0 = ld[k].c0, c1 = ld[k].c1, s0 = ld[k].s0, s1 = ld[k].s1;
;                     f32x4 o1a = a0 * c0 - b0 * s0, o1b = a1 * c1 - b1 * s1, o2a = b0 * c0 + a0 * s0, o2b = b1 * c1 + a1 * s1;
;                     if (pn < 2) {
;                         o1a *= QS; o1b *= QS; o2a *= QS; o2b *= QS;
;                         bf16_t* q = Q + (size_t)row * 512 + (4 * pn + wc) * 64 + fq * 8;
;                         gst<u32x4>(q, pk8(o1a, o1b)); gst<u32x4>(q + 32, pk8(o2a, o2b));
	v_pk_mul_f32 v[234:235], v[124:125], v[226:227]
	v_pk_mul_f32 v[236:237], v[126:127], v[228:229]
	v_pk_mul_f32 v[238:239], v[120:121], v[230:231]
	v_pk_mul_f32 v[240:241], v[122:123], v[232:233]
	v_pk_fma_f32 v[234:235], v[140:141], v[218:219], v[234:235] neg_lo:[0,0,1] neg_hi:[0,0,1]
	v_pk_fma_f32 v[236:237], v[142:143], v[220:221], v[236:237] neg_lo:[0,0,1] neg_hi:[0,0,1]
	v_pk_fma_f32 v[238:239], v[136:137], v[222:223], v[238:239] neg_lo:[0,0,1] neg_hi:[0,0,1]
	v_pk_fma_f32 v[240:241], v[138:139], v[224:225], v[240:241] neg_lo:[0,0,1] neg_hi:[0,0,1]
	v_pk_mul_f32 v[226:227], v[140:141], v[226:227]
	v_pk_mul_f32 v[228:229], v[142:143], v[228:229]
	v_pk_mul_f32 v[230:231], v[136:137], v[230:231]
	v_pk_mul_f32 v[232:233], v[138:139], v[232:233]
	v_pk_fma_f32 v[226:227], v[124:125], v[218:219], v[226:227]
	v_pk_fma_f32 v[228:229], v[126:127], v[220:221], v[228:229]
	v_pk_fma_f32 v[230:231], v[120:121], v[222:223], v[230:231]
	v_pk_fma_f32 v[232:233], v[122:123], v[224:225], v[232:233]
	v_pk_mul_f32 v[234:235], v[234:235], s[30:31]
	v_pk_mul_f32 v[236:237], v[236:237], s[30:31]
	v_pk_mul_f32 v[238:239], v[238:239], s[30:31]
	v_pk_mul_f32 v[240:241], v[240:241], s[30:31]
	v_pk_mul_f32 v[226:227], v[226:227], s[30:31]
	v_pk_mul_f32 v[228:229], v[228:229], s[30:31]
	v_pk_mul_f32 v[230:231], v[230:231], s[30:31]
	v_pk_mul_f32 v[232:233], v[232:233], s[30:31]
	v_cvt_pk_bf16_f32 v140, v234, v235
	v_cvt_pk_bf16_f32 v141, v236, v237
	v_cvt_pk_bf16_f32 v142, v238, v239
	v_cvt_pk_bf16_f32 v143, v240, v241
	global_store_dwordx4 v214, v[140:143], s[16:17]
	v_cvt_pk_bf16_f32 v124, v226, v227
	v_cvt_pk_bf16_f32 v125, v228, v229
	v_cvt_pk_bf16_f32 v126, v230, v231
	v_cvt_pk_bf16_f32 v127, v232, v233
	global_store_dwordx4 v214, v[124:127], s[16:17] offset:64
	s_add_u32 s16, s16, 0x4000
	s_addc_u32 s17, s17, 0
	global_load_dwordx4 v[218:221], v252, s[12:13]
	global_load_dwordx4 v[222:225], v252, s[12:13] offset:16
	global_load_dwordx4 v[226:229], v252, s[12:13] offset:128
	global_load_dwordx4 v[230:233], v252, s[12:13] offset:144
	v_add_u32_e32 v252, s7, v252
	v_pk_mul_f32 v[92:93], v[92:93], v[180:181] op_sel_hi:[1,0]
	v_pk_mul_f32 v[94:95], v[94:95], v[180:181] op_sel_hi:[1,0]
	v_pk_mul_f32 v[88:89], v[88:89], v[180:181] op_sel_hi:[1,0]
	v_pk_mul_f32 v[90:91], v[90:91], v[180:181] op_sel_hi:[1,0]
	v_pk_mul_f32 v[84:85], v[84:85], v[180:181] op_sel_hi:[1,0]
	v_pk_mul_f32 v[86:87], v[86:87], v[180:181] op_sel_hi:[1,0]
	v_pk_mul_f32 v[80:81], v[80:81], v[180:181] op_sel_hi:[1,0]
	v_pk_mul_f32 v[82:83], v[82:83], v[180:181] op_sel_hi:[1,0]
	s_waitcnt vmcnt(16)
	v_pk_mul_f32 v[234:235], v[84:85], v[152:153]
	v_pk_mul_f32 v[236:237], v[86:87], v[154:155]
	v_pk_mul_f32 v[238:239], v[80:81], v[156:157]
	v_pk_mul_f32 v[240:241], v[82:83], v[158:159]
	v_pk_fma_f32 v[234:235], v[92:93], v[144:145], v[234:235] neg_lo:[0,0,1] neg_hi:[0,0,1]
	v_pk_fma_f32 v[236:237], v[94:95], v[146:147], v[236:237] neg_lo:[0,0,1] neg_hi:[0,0,1]
	v_pk_fma_f32 v[238:239], v[88:89], v[148:149], v[238:239] neg_lo:[0,0,1] neg_hi:[0,0,1]
	v_pk_fma_f32 v[240:241], v[90:91], v[150:151], v[240:241] neg_lo:[0,0,1] neg_hi:[0,0,1]
	v_pk_mul_f32 v[152:153], v[92:93], v[152:153]
	v_pk_mul_f32 v[154:155], v[94:95], v[154:155]
	v_pk_mul_f32 v[156:157], v[88:89], v[156:157]
	v_pk_mul_f32 v[158:159], v[90:91], v[158:159]
	v_pk_fma_f32 v[152:153], v[84:85], v[144:145], v[152:153]
	v_pk_fma_f32 v[154:155], v[86:87], v[146:147], v[154:155]
	v_pk_fma_f32 v[156:157], v[80:81], v[148:149], v[156:157]
	v_pk_fma_f32 v[158:159], v[82:83], v[150:151], v[158:159]
	v_pk_mul_f32 v[234:235], v[234:235], s[30:31]
	v_pk_mul_f32 v[236:237], v[236:237], s[30:31]
	v_pk_mul_f32 v[238:239], v[238:239], s[30:31]
	v_pk_mul_f32 v[240:241], v[240:241], s[30:31]
	v_pk_mul_f32 v[152:153], v[152:153], s[30:31]
	v_pk_mul_f32 v[154:155], v[154:155], s[30:31]
	v_pk_mul_f32 v[156:157], v[156:157], s[30:31]
	v_pk_mul_f32 v[158:159], v[158:159], s[30:31]
	v_cvt_pk_bf16_f32 v92, v234, v235
	v_cvt_pk_bf16_f32 v93, v236, v237
	v_cvt_pk_bf16_f32 v94, v238, v239
	v_cvt_pk_bf16_f32 v95, v240, v241
	global_store_dwordx4 v214, v[92:95], s[16:17]
	v_cvt_pk_bf16_f32 v84, v152, v153
	v_cvt_pk_bf16_f32 v85, v154, v155
	v_cvt_pk_bf16_f32 v86, v156, v157
	v_cvt_pk_bf16_f32 v87, v158, v159
	global_store_dwordx4 v214, v[84:87], s[16:17] offset:64
	s_add_u32 s16, s16, 0x4000
	s_addc_u32 s17, s17, 0
	global_load_dwordx4 v[144:147], v252, s[12:13]
	global_load_dwordx4 v[148:151], v252, s[12:13] offset:16
	global_load_dwordx4 v[152:155], v252, s[12:13] offset:128
	global_load_dwordx4 v[156:159], v252, s[12:13] offset:144
	v_add_u32_e32 v252, s7, v252
	v_pk_mul_f32 v[76:77], v[76:77], v[182:183] op_sel_hi:[1,0]
	v_pk_mul_f32 v[78:79], v[78:79], v[182:183] op_sel_hi:[1,0]
	v_pk_mul_f32 v[72:73], v[72:73], v[182:183] op_sel_hi:[1,0]
	v_pk_mul_f32 v[74:75], v[74:75], v[182:183] op_sel_hi:[1,0]
	v_pk_mul_f32 v[68:69], v[68:69], v[182:183] op_sel_hi:[1,0]
	v_pk_mul_f32 v[70:71], v[70:71], v[182:183] op_sel_hi:[1,0]
	v_pk_mul_f32 v[64:65], v[64:65], v[182:183] op_sel_hi:[1,0]
	v_pk_mul_f32 v[66:67], v[66:67], v[182:183] op_sel_hi:[1,0]
	s_waitcnt vmcnt(18)
; __device__ __forceinline__ u32x4 pk8(f32x4 a, f32x4 b) { u32x4 w; w.x = pk2(a[0], a[1]); w.y = pk2(a[2], a[3]); w.z = pk2(b[0], b[1]); w.w = pk2(b[2], b[3]); return w; }
;     __device__ __forceinline__ void operator()(const f32x4 (&acc)[2][2][4][2], const pg8::Unit& u, int wr, int wc, int fr_, int fq_) const {
;     ...
;                 const f32x4 a0 = acc[ai][0][m][0] * rs, a1 = acc[ai][0][m][1] * rs, b0 = acc[ai][1][m][0] * rs, b1 = acc[ai][1][m][1] * rs;
;                 if (rope) {
;                     const f32x4 c0 = ld[k].c0, c1 = ld[k].c1, s0 = ld[k].s0, s1 = ld[k].s1;
;                     f32x4 o1a = a0 * c0 - b0 * s0, o1b = a1 * c1 - b1 * s1, o2a = b0 * c0 + a0 * s0, o2b = b1 * c1 + a1 * s1;
;                     if (pn < 2) {
;                         o1a *= QS; o1b *= QS; o2a *= QS; o2b *= QS;
;                         bf16_t* q = Q + (size_t)row * 512 + (4 * pn + wc) * 64 + fq * 8;
;                         gst<u32x4>(q, pk8(o1a, o1b)); gst<u32x4>(q + 32, pk8(o2a, o2b));
	v_pk_mul_f32 v[234:235], v[68:69], v[168:169]
	v_pk_mul_f32 v[236:237], v[70:71], v[170:171]
	v_pk_mul_f32 v[238:239], v[64:65], v[172:173]
	v_pk_mul_f32 v[240:241], v[66:67], v[174:175]
	v_pk_fma_f32 v[234:235], v[76:77], v[160:161], v[234:235] neg_lo:[0,0,1] neg_hi:[0,0,1]
	v_pk_fma_f32 v[236:237], v[78:79], v[162:163], v[236:237] neg_lo:[0,0,1] neg_hi:[0,0,1]
	v_pk_fma_f32 v[238:239], v[72:73], v[164:165], v[238:239] neg_lo:[0,0,1] neg_hi:[0,0,1]
	v_pk_fma_f32 v[240:241], v[74:75], v[166:167], v[240:241] neg_lo:[0,0,1] neg_hi:[0,0,1]
	v_pk_mul_f32 v[168:169], v[76:77], v[168:169]
	v_pk_mul_f32 v[170:171], v[78:79], v[170:171]
	v_pk_mul_f32 v[172:173], v[72:73], v[172:173]
	v_pk_mul_f32 v[174:175], v[74:75], v[174:175]
	v_pk_fma_f32 v[168:169], v[68:69], v[160:161], v[168:169]
	v_pk_fma_f32 v[170:171], v[70:71], v[162:163], v[170:171]
	v_pk_fma_f32 v[172:173], v[64:65], v[164:165], v[172:173]
	v_pk_fma_f32 v[174:175], v[66:67], v[166:167], v[174:175]
	v_pk_mul_f32 v[234:235], v[234:235], s[30:31]
	v_pk_mul_f32 v[236:237], v[236:237], s[30:31]
	v_pk_mul_f32 v[238:239], v[238:239], s[30:31]
	v_pk_mul_f32 v[240:241], v[240:241], s[30:31]
	v_pk_mul_f32 v[168:169], v[168:169], s[30:31]
	v_pk_mul_f32 v[170:171], v[170:171], s[30:31]
	v_pk_mul_f32 v[172:173], v[172:173], s[30:31]
	v_pk_mul_f32 v[174:175], v[174:175], s[30:31]
	v_cvt_pk_bf16_f32 v76, v234, v235
	v_cvt_pk_bf16_f32 v77, v236, v237
	v_cvt_pk_bf16_f32 v78, v238, v239
	v_cvt_pk_bf16_f32 v79, v240, v241
	global_store_dwordx4 v214, v[76:79], s[16:17]
	v_cvt_pk_bf16_f32 v68, v168, v169
	v_cvt_pk_bf16_f32 v69, v170, v171
	v_cvt_pk_bf16_f32 v70, v172, v173
	v_cvt_pk_bf16_f32 v71, v174, v175
	global_store_dwordx4 v214, v[68:71], s[16:17] offset:64
	s_add_u32 s16, s16, 0x14000
	s_addc_u32 s17, s17, 0
	global_load_dwordx4 v[160:163], v252, s[12:13]
	global_load_dwordx4 v[164:167], v252, s[12:13] offset:16
	global_load_dwordx4 v[168:171], v252, s[12:13] offset:128
	global_load_dwordx4 v[172:175], v252, s[12:13] offset:144
	v_pk_mul_f32 v[60:61], v[60:61], v[184:185] op_sel_hi:[1,0]
	v_pk_mul_f32 v[62:63], v[62:63], v[184:185] op_sel_hi:[1,0]
	v_pk_mul_f32 v[56:57], v[56:57], v[184:185] op_sel_hi:[1,0]
	v_pk_mul_f32 v[58:59], v[58:59], v[184:185] op_sel_hi:[1,0]
	v_pk_mul_f32 v[52:53], v[52:53], v[184:185] op_sel_hi:[1,0]
	v_pk_mul_f32 v[54:55], v[54:55], v[184:185] op_sel_hi:[1,0]
	v_pk_mul_f32 v[48:49], v[48:49], v[184:185] op_sel_hi:[1,0]
	v_pk_mul_f32 v[50:51], v[50:51], v[184:185] op_sel_hi:[1,0]
	s_waitcnt vmcnt(18)
	v_pk_mul_f32 v[234:235], v[52:53], v[104:105]
	v_pk_mul_f32 v[236:237], v[54:55], v[106:107]
	v_pk_mul_f32 v[238:239], v[48:49], v[108:109]
	v_pk_mul_f32 v[240:241], v[50:51], v[110:111]
	v_pk_fma_f32 v[234:235], v[60:61], v[96:97], v[234:235] neg_lo:[0,0,1] neg_hi:[0,0,1]
	v_pk_fma_f32 v[236:237], v[62:63], v[98:99], v[236:237] neg_lo:[0,0,1] neg_hi:[0,0,1]
	v_pk_fma_f32 v[238:239], v[56:57], v[100:101], v[238:239] neg_lo:[0,0,1] neg_hi:[0,0,1]
	v_pk_fma_f32 v[240:241], v[58:59], v[102:103], v[240:241] neg_lo:[0,0,1] neg_hi:[0,0,1]
	v_pk_mul_f32 v[104:105], v[60:61], v[104:105]
	v_pk_mul_f32 v[106:107], v[62:63], v[106:107]
	v_pk_mul_f32 v[108:109], v[56:57], v[108:109]
	v_pk_mul_f32 v[110:111], v[58:59], v[110:111]
	v_pk_fma_f32 v[104:105], v[52:53], v[96:97], v[104:105]
	v_pk_fma_f32 v[106:107], v[54:55], v[98:99], v[106:107]
	v_pk_fma_f32 v[108:109], v[48:49], v[100:101], v[108:109]
	v_pk_fma_f32 v[110:111], v[50:51], v[102:103], v[110:111]
	v_pk_mul_f32 v[234:235], v[234:235], s[30:31]
	v_pk_mul_f32 v[236:237], v[236:237], s[30:31]
	v_pk_mul_f32 v[238:239], v[238:239], s[30:31]
	v_pk_mul_f32 v[240:241], v[240:241], s[30:31]
	v_pk_mul_f32 v[104:105], v[104:105], s[30:31]
	v_pk_mul_f32 v[106:107], v[106:107], s[30:31]
	v_pk_mul_f32 v[108:109], v[108:109], s[30:31]
	v_pk_mul_f32 v[110:111], v[110:111], s[30:31]
	v_cvt_pk_bf16_f32 v60, v234, v235
	v_cvt_pk_bf16_f32 v61, v236, v237
	v_cvt_pk_bf16_f32 v62, v238, v239
	v_cvt_pk_bf16_f32 v63, v240, v241
	global_store_dwordx4 v214, v[60:63], s[16:17]
	v_cvt_pk_bf16_f32 v52, v104, v105
	v_cvt_pk_bf16_f32 v53, v106, v107
	v_cvt_pk_bf16_f32 v54, v108, v109
	v_cvt_pk_bf16_f32 v55, v110, v111
	global_store_dwordx4 v214, v[52:55], s[16:17] offset:64
	s_add_u32 s16, s16, 0x4000
	s_addc_u32 s17, s17, 0
	v_pk_mul_f32 v[44:45], v[44:45], v[186:187] op_sel_hi:[1,0]
	v_pk_mul_f32 v[46:47], v[46:47], v[186:187] op_sel_hi:[1,0]
	v_pk_mul_f32 v[40:41], v[40:41], v[186:187] op_sel_hi:[1,0]
	v_pk_mul_f32 v[42:43], v[42:43], v[186:187] op_sel_hi:[1,0]
	v_pk_mul_f32 v[36:37], v[36:37], v[186:187] op_sel_hi:[1,0]
	v_pk_mul_f32 v[38:39], v[38:39], v[186:187] op_sel_hi:[1,0]
	v_pk_mul_f32 v[32:33], v[32:33], v[186:187] op_sel_hi:[1,0]
	v_pk_mul_f32 v[34:35], v[34:35], v[186:187] op_sel_hi:[1,0]
	s_waitcnt vmcnt(14)
; __device__ __forceinline__ u32x4 pk8(f32x4 a, f32x4 b) { u32x4 w; w.x = pk2(a[0], a[1]); w.y = pk2(a[2], a[3]); w.z = pk2(b[0], b[1]); w.w = pk2(b[2], b[3]); return w; }
;     __device__ __forceinline__ void operator()(const f32x4 (&acc)[2][2][4][2], const pg8::Unit& u, int wr, int wc, int fr_, int fq_) const {
;     ...
;                 const f32x4 a0 = acc[ai][0][m][0] * rs, a1 = acc[ai][0][m][1] * rs, b0 = acc[ai][1][m][0] * rs, b1 = acc[ai][1][m][1] * rs;
;                 if (rope) {
;                     const f32x4 c0 = ld[k].c0, c1 = ld[k].c1, s0 = ld[k].s0, s1 = ld[k].s1;
;                     f32x4 o1a = a0 * c0 - b0 * s0, o1b = a1 * c1 - b1 * s1, o2a = b0 * c0 + a0 * s0, o2b = b1 * c1 + a1 * s1;
;                     if (pn < 2) {
;                         o1a *= QS; o1b *= QS; o2a *= QS; o2b *= QS;
;                         bf16_t* q = Q + (size_t)row * 512 + (4 * pn + wc) * 64 + fq * 8;
;                         gst<u32x4>(q, pk8(o1a, o1b)); gst<u32x4>(q + 32, pk8(o2a, o2b));
	v_pk_mul_f32 v[234:235], v[36:37], v[226:227]
	v_pk_mul_f32 v[236:237], v[38:39], v[228:229]
	v_pk_mul_f32 v[238:239], v[32:33], v[230:231]
	v_pk_mul_f32 v[240:241], v[34:35], v[232:233]
	v_pk_fma_f32 v[234:235], v[44:45], v[218:219], v[234:235] neg_lo:[0,0,1] neg_hi:[0,0,1]
	v_pk_fma_f32 v[236:237], v[46:47], v[220:221], v[236:237] neg_lo:[0,0,1] neg_hi:[0,0,1]
	v_pk_fma_f32 v[238:239], v[40:41], v[222:223], v[238:239] neg_lo:[0,0,1] neg_hi:[0,0,1]
	v_pk_fma_f32 v[240:241], v[42:43], v[224:225], v[240:241] neg_lo:[0,0,1] neg_hi:[0,0,1]
	v_pk_mul_f32 v[226:227], v[44:45], v[226:227]
	v_pk_mul_f32 v[228:229], v[46:47], v[228:229]
	v_pk_mul_f32 v[230:231], v[40:41], v[230:231]
	v_pk_mul_f32 v[232:233], v[42:43], v[232:233]
	v_pk_fma_f32 v[226:227], v[36:37], v[218:219], v[226:227]
	v_pk_fma_f32 v[228:229], v[38:39], v[220:221], v[228:229]
	v_pk_fma_f32 v[230:231], v[32:33], v[222:223], v[230:231]
	v_pk_fma_f32 v[232:233], v[34:35], v[224:225], v[232:233]
	v_pk_mul_f32 v[234:235], v[234:235], s[30:31]
	v_pk_mul_f32 v[236:237], v[236:237], s[30:31]
	v_pk_mul_f32 v[238:239], v[238:239], s[30:31]
	v_pk_mul_f32 v[240:241], v[240:241], s[30:31]
	v_pk_mul_f32 v[226:227], v[226:227], s[30:31]
	v_pk_mul_f32 v[228:229], v[228:229], s[30:31]
	v_pk_mul_f32 v[230:231], v[230:231], s[30:31]
	v_pk_mul_f32 v[232:233], v[232:233], s[30:31]
	v_cvt_pk_bf16_f32 v44, v234, v235
	v_cvt_pk_bf16_f32 v45, v236, v237
	v_cvt_pk_bf16_f32 v46, v238, v239
	v_cvt_pk_bf16_f32 v47, v240, v241
	global_store_dwordx4 v214, v[44:47], s[16:17]
	v_cvt_pk_bf16_f32 v36, v226, v227
	v_cvt_pk_bf16_f32 v37, v228, v229
	v_cvt_pk_bf16_f32 v38, v230, v231
	v_cvt_pk_bf16_f32 v39, v232, v233
	global_store_dwordx4 v214, v[36:39], s[16:17] offset:64
	s_add_u32 s16, s16, 0x4000
	s_addc_u32 s17, s17, 0
	v_pk_mul_f32 v[28:29], v[28:29], v[188:189] op_sel_hi:[1,0]
	v_pk_mul_f32 v[30:31], v[30:31], v[188:189] op_sel_hi:[1,0]
	v_pk_mul_f32 v[24:25], v[24:25], v[188:189] op_sel_hi:[1,0]
	v_pk_mul_f32 v[26:27], v[26:27], v[188:189] op_sel_hi:[1,0]
	v_pk_mul_f32 v[20:21], v[20:21], v[188:189] op_sel_hi:[1,0]
	v_pk_mul_f32 v[22:23], v[22:23], v[188:189] op_sel_hi:[1,0]
	v_pk_mul_f32 v[16:17], v[16:17], v[188:189] op_sel_hi:[1,0]
	v_pk_mul_f32 v[18:19], v[18:19], v[188:189] op_sel_hi:[1,0]
	s_waitcnt vmcnt(10)
	v_pk_mul_f32 v[234:235], v[20:21], v[152:153]
	v_pk_mul_f32 v[236:237], v[22:23], v[154:155]
	v_pk_mul_f32 v[238:239], v[16:17], v[156:157]
	v_pk_mul_f32 v[240:241], v[18:19], v[158:159]
	v_pk_fma_f32 v[234:235], v[28:29], v[144:145], v[234:235] neg_lo:[0,0,1] neg_hi:[0,0,1]
	v_pk_fma_f32 v[236:237], v[30:31], v[146:147], v[236:237] neg_lo:[0,0,1] neg_hi:[0,0,1]
	v_pk_fma_f32 v[238:239], v[24:25], v[148:149], v[238:239] neg_lo:[0,0,1] neg_hi:[0,0,1]
	v_pk_fma_f32 v[240:241], v[26:27], v[150:151], v[240:241] neg_lo:[0,0,1] neg_hi:[0,0,1]
	v_pk_mul_f32 v[152:153], v[28:29], v[152:153]
	v_pk_mul_f32 v[154:155], v[30:31], v[154:155]
	v_pk_mul_f32 v[156:157], v[24:25], v[156:157]
	v_pk_mul_f32 v[158:159], v[26:27], v[158:159]
	v_pk_fma_f32 v[152:153], v[20:21], v[144:145], v[152:153]
	v_pk_fma_f32 v[154:155], v[22:23], v[146:147], v[154:155]
	v_pk_fma_f32 v[156:157], v[16:17], v[148:149], v[156:157]
	v_pk_fma_f32 v[158:159], v[18:19], v[150:151], v[158:159]
	v_pk_mul_f32 v[234:235], v[234:235], s[30:31]
	v_pk_mul_f32 v[236:237], v[236:237], s[30:31]
	v_pk_mul_f32 v[238:239], v[238:239], s[30:31]
	v_pk_mul_f32 v[240:241], v[240:241], s[30:31]
	v_pk_mul_f32 v[152:153], v[152:153], s[30:31]
	v_pk_mul_f32 v[154:155], v[154:155], s[30:31]
	v_pk_mul_f32 v[156:157], v[156:157], s[30:31]
	v_pk_mul_f32 v[158:159], v[158:159], s[30:31]
	v_cvt_pk_bf16_f32 v28, v234, v235
	v_cvt_pk_bf16_f32 v29, v236, v237
	v_cvt_pk_bf16_f32 v30, v238, v239
	v_cvt_pk_bf16_f32 v31, v240, v241
	global_store_dwordx4 v214, v[28:31], s[16:17]
	v_cvt_pk_bf16_f32 v20, v152, v153
	v_cvt_pk_bf16_f32 v21, v154, v155
	v_cvt_pk_bf16_f32 v22, v156, v157
	v_cvt_pk_bf16_f32 v23, v158, v159
	global_store_dwordx4 v214, v[20:23], s[16:17] offset:64
	s_add_u32 s16, s16, 0x4000
	s_addc_u32 s17, s17, 0
	v_pk_mul_f32 v[12:13], v[12:13], v[190:191] op_sel_hi:[1,0]
	v_pk_mul_f32 v[14:15], v[14:15], v[190:191] op_sel_hi:[1,0]
	v_pk_mul_f32 v[8:9], v[8:9], v[190:191] op_sel_hi:[1,0]
	v_pk_mul_f32 v[10:11], v[10:11], v[190:191] op_sel_hi:[1,0]
	v_pk_mul_f32 v[4:5], v[4:5], v[190:191] op_sel_hi:[1,0]
	v_pk_mul_f32 v[6:7], v[6:7], v[190:191] op_sel_hi:[1,0]
	v_pk_mul_f32 v[0:1], v[0:1], v[190:191] op_sel_hi:[1,0]
	v_pk_mul_f32 v[2:3], v[2:3], v[190:191] op_sel_hi:[1,0]
	s_waitcnt vmcnt(6)
	v_pk_mul_f32 v[234:235], v[4:5], v[168:169]
	v_pk_mul_f32 v[236:237], v[6:7], v[170:171]
	v_pk_mul_f32 v[238:239], v[0:1], v[172:173]
	v_pk_mul_f32 v[240:241], v[2:3], v[174:175]
	v_pk_fma_f32 v[234:235], v[12:13], v[160:161], v[234:235] neg_lo:[0,0,1] neg_hi:[0,0,1]
	v_pk_fma_f32 v[236:237], v[14:15], v[162:163], v[236:237] neg_lo:[0,0,1] neg_hi:[0,0,1]
	v_pk_fma_f32 v[238:239], v[8:9], v[164:165], v[238:239] neg_lo:[0,0,1] neg_hi:[0,0,1]
	v_pk_fma_f32 v[240:241], v[10:11], v[166:167], v[240:241] neg_lo:[0,0,1] neg_hi:[0,0,1]
	v_pk_mul_f32 v[168:169], v[12:13], v[168:169]
	v_pk_mul_f32 v[170:171], v[14:15], v[170:171]
	v_pk_mul_f32 v[172:173], v[8:9], v[172:173]
	v_pk_mul_f32 v[174:175], v[10:11], v[174:175]
	v_pk_fma_f32 v[168:169], v[4:5], v[160:161], v[168:169]
	v_pk_fma_f32 v[170:171], v[6:7], v[162:163], v[170:171]
	v_pk_fma_f32 v[172:173], v[0:1], v[164:165], v[172:173]
	v_pk_fma_f32 v[174:175], v[2:3], v[166:167], v[174:175]
	v_pk_mul_f32 v[234:235], v[234:235], s[30:31]
	v_pk_mul_f32 v[236:237], v[236:237], s[30:31]
	v_pk_mul_f32 v[238:239], v[238:239], s[30:31]
	v_pk_mul_f32 v[240:241], v[240:241], s[30:31]
	v_pk_mul_f32 v[168:169], v[168:169], s[30:31]
	v_pk_mul_f32 v[170:171], v[170:171], s[30:31]
	v_pk_mul_f32 v[172:173], v[172:173], s[30:31]
	v_pk_mul_f32 v[174:175], v[174:175], s[30:31]
	v_cvt_pk_bf16_f32 v12, v234, v235
	v_cvt_pk_bf16_f32 v13, v236, v237
	v_cvt_pk_bf16_f32 v14, v238, v239
	v_cvt_pk_bf16_f32 v15, v240, v241
	global_store_dwordx4 v214, v[12:15], s[16:17]
	v_cvt_pk_bf16_f32 v4, v168, v169
	v_cvt_pk_bf16_f32 v5, v170, v171
	v_cvt_pk_bf16_f32 v6, v172, v173
	v_cvt_pk_bf16_f32 v7, v174, v175
	global_store_dwordx4 v214, v[4:7], s[16:17] offset:64
	s_branch .LBB0_580
; __device__ __forceinline__ u32x4 pk8(f32x4 a, f32x4 b) { u32x4 w; w.x = pk2(a[0], a[1]); w.y = pk2(a[2], a[3]); w.z = pk2(b[0], b[1]); w.w = pk2(b[2], b[3]); return w; }
; __device__ __forceinline__ f32x4 silu4(f32x4 x) { f32x4 r; for (int i = 0; i < 4; ++i) r[i] = x[i] * sigm(x[i]); return r; }
; __device__ __forceinline__ float sigm(float x) { return __builtin_amdgcn_rcpf(1.f + __builtin_amdgcn_exp2f(-x * LOG2E)); }
;     __device__ __forceinline__ void operator()(const f32x4 (&acc)[2][2][4][2], const pg8::Unit& u, int wr, int wc, int fr_, int fq_) const {
;     ...
;                 } else if (pn < 5) {
;                     bf16_t* p = SGA + (size_t)row * 512 + (pn - 3) * 256 + cw;
;                     gst<u32x4>(p, pk8(silu4(a0), silu4(a1))); gst<u32x4>(p + 128, pk8(silu4(b0), silu4(b1)));
.Lme_spath:
	v_pk_mul_f32 v[132:133], v[132:133], v[176:177] op_sel_hi:[1,0]
	v_pk_mul_f32 v[134:135], v[134:135], v[176:177] op_sel_hi:[1,0]
	v_pk_mul_f32 v[128:129], v[128:129], v[176:177] op_sel_hi:[1,0]
	v_pk_mul_f32 v[130:131], v[130:131], v[176:177] op_sel_hi:[1,0]
	v_pk_mul_f32 v[116:117], v[116:117], v[176:177] op_sel_hi:[1,0]
	v_pk_mul_f32 v[118:119], v[118:119], v[176:177] op_sel_hi:[1,0]
	v_pk_mul_f32 v[112:113], v[112:113], v[176:177] op_sel_hi:[1,0]
	v_pk_mul_f32 v[114:115], v[114:115], v[176:177] op_sel_hi:[1,0]
	v_pk_mul_f32 v[96:97], v[132:133], s[30:31]
	v_pk_mul_f32 v[98:99], v[134:135], s[30:31]
	v_pk_mul_f32 v[100:101], v[128:129], s[30:31]
	v_pk_mul_f32 v[102:103], v[130:131], s[30:31]
	v_exp_f32_e32 v96, v96
	v_exp_f32_e32 v97, v97
	v_exp_f32_e32 v98, v98
	v_exp_f32_e32 v99, v99
	v_exp_f32_e32 v100, v100
	v_exp_f32_e32 v101, v101
	v_exp_f32_e32 v102, v102
	v_exp_f32_e32 v103, v103
	v_pk_add_f32 v[96:97], v[96:97], 1.0 op_sel_hi:[1,0]
	v_pk_add_f32 v[98:99], v[98:99], 1.0 op_sel_hi:[1,0]
	v_pk_add_f32 v[100:101], v[100:101], 1.0 op_sel_hi:[1,0]
	v_pk_add_f32 v[102:103], v[102:103], 1.0 op_sel_hi:[1,0]
	v_rcp_f32_e32 v96, v96
	v_rcp_f32_e32 v97, v97
	v_rcp_f32_e32 v98, v98
	v_rcp_f32_e32 v99, v99
	v_rcp_f32_e32 v100, v100
	v_rcp_f32_e32 v101, v101
	v_rcp_f32_e32 v102, v102
	v_rcp_f32_e32 v103, v103
	v_pk_mul_f32 v[132:133], v[132:133], v[96:97]
	v_pk_mul_f32 v[134:135], v[134:135], v[98:99]
	v_pk_mul_f32 v[128:129], v[128:129], v[100:101]
	v_pk_mul_f32 v[130:131], v[130:131], v[102:103]
	v_pk_mul_f32 v[96:97], v[116:117], s[30:31]
	v_pk_mul_f32 v[98:99], v[118:119], s[30:31]
	v_pk_mul_f32 v[100:101], v[112:113], s[30:31]
	v_pk_mul_f32 v[102:103], v[114:115], s[30:31]
	v_exp_f32_e32 v96, v96
	v_exp_f32_e32 v97, v97
	v_exp_f32_e32 v98, v98
	v_exp_f32_e32 v99, v99
	v_exp_f32_e32 v100, v100
	v_exp_f32_e32 v101, v101
	v_exp_f32_e32 v102, v102
	v_exp_f32_e32 v103, v103
	v_pk_add_f32 v[96:97], v[96:97], 1.0 op_sel_hi:[1,0]
	v_pk_add_f32 v[98:99], v[98:99], 1.0 op_sel_hi:[1,0]
	v_pk_add_f32 v[100:101], v[100:101], 1.0 op_sel_hi:[1,0]
	v_pk_add_f32 v[102:103], v[102:103], 1.0 op_sel_hi:[1,0]
	v_rcp_f32_e32 v96, v96
	v_rcp_f32_e32 v97, v97
	v_rcp_f32_e32 v98, v98
	v_rcp_f32_e32 v99, v99
	v_rcp_f32_e32 v100, v100
	v_rcp_f32_e32 v101, v101
	v_rcp_f32_e32 v102, v102
	v_rcp_f32_e32 v103, v103
	v_pk_mul_f32 v[116:117], v[116:117], v[96:97]
	v_pk_mul_f32 v[118:119], v[118:119], v[98:99]
	v_pk_mul_f32 v[112:113], v[112:113], v[100:101]
	v_pk_mul_f32 v[114:115], v[114:115], v[102:103]
	v_cvt_pk_bf16_f32 v104, v132, v133
	v_cvt_pk_bf16_f32 v105, v134, v135
	v_cvt_pk_bf16_f32 v106, v128, v129
	v_cvt_pk_bf16_f32 v107, v130, v131
	global_store_dwordx4 v214, v[104:107], s[16:17]
	v_cvt_pk_bf16_f32 v218, v116, v117
	v_cvt_pk_bf16_f32 v219, v118, v119
	v_cvt_pk_bf16_f32 v220, v112, v113
	v_cvt_pk_bf16_f32 v221, v114, v115
	global_store_dwordx4 v214, v[218:221], s[16:17] offset:256
	s_add_u32 s16, s16, 0x4000
	s_addc_u32 s17, s17, 0
	v_pk_mul_f32 v[140:141], v[140:141], v[178:179] op_sel_hi:[1,0]
	v_pk_mul_f32 v[142:143], v[142:143], v[178:179] op_sel_hi:[1,0]
	v_pk_mul_f32 v[136:137], v[136:137], v[178:179] op_sel_hi:[1,0]
	v_pk_mul_f32 v[138:139], v[138:139], v[178:179] op_sel_hi:[1,0]
	v_pk_mul_f32 v[124:125], v[124:125], v[178:179] op_sel_hi:[1,0]
	v_pk_mul_f32 v[126:127], v[126:127], v[178:179] op_sel_hi:[1,0]
	v_pk_mul_f32 v[120:121], v[120:121], v[178:179] op_sel_hi:[1,0]
	v_pk_mul_f32 v[122:123], v[122:123], v[178:179] op_sel_hi:[1,0]
	v_pk_mul_f32 v[96:97], v[140:141], s[30:31]
	v_pk_mul_f32 v[98:99], v[142:143], s[30:31]
	v_pk_mul_f32 v[100:101], v[136:137], s[30:31]
	v_pk_mul_f32 v[102:103], v[138:139], s[30:31]
	v_exp_f32_e32 v96, v96
	v_exp_f32_e32 v97, v97
	v_exp_f32_e32 v98, v98
	v_exp_f32_e32 v99, v99
	v_exp_f32_e32 v100, v100
	v_exp_f32_e32 v101, v101
	v_exp_f32_e32 v102, v102
	v_exp_f32_e32 v103, v103
	v_pk_add_f32 v[96:97], v[96:97], 1.0 op_sel_hi:[1,0]
	v_pk_add_f32 v[98:99], v[98:99], 1.0 op_sel_hi:[1,0]
	v_pk_add_f32 v[100:101], v[100:101], 1.0 op_sel_hi:[1,0]
	v_pk_add_f32 v[102:103], v[102:103], 1.0 op_sel_hi:[1,0]
	v_rcp_f32_e32 v96, v96
	v_rcp_f32_e32 v97, v97
	v_rcp_f32_e32 v98, v98
	v_rcp_f32_e32 v99, v99
	v_rcp_f32_e32 v100, v100
	v_rcp_f32_e32 v101, v101
	v_rcp_f32_e32 v102, v102
	v_rcp_f32_e32 v103, v103
	v_pk_mul_f32 v[140:141], v[140:141], v[96:97]
	v_pk_mul_f32 v[142:143], v[142:143], v[98:99]
	v_pk_mul_f32 v[136:137], v[136:137], v[100:101]
	v_pk_mul_f32 v[138:139], v[138:139], v[102:103]
	v_pk_mul_f32 v[96:97], v[124:125], s[30:31]
	v_pk_mul_f32 v[98:99], v[126:127], s[30:31]
	v_pk_mul_f32 v[100:101], v[120:121], s[30:31]
	v_pk_mul_f32 v[102:103], v[122:123], s[30:31]
	v_exp_f32_e32 v96, v96
	v_exp_f32_e32 v97, v97
	v_exp_f32_e32 v98, v98
	v_exp_f32_e32 v99, v99
	v_exp_f32_e32 v100, v100
	v_exp_f32_e32 v101, v101
	v_exp_f32_e32 v102, v102
	v_exp_f32_e32 v103, v103
	v_pk_add_f32 v[96:97], v[96:97], 1.0 op_sel_hi:[1,0]
	v_pk_add_f32 v[98:99], v[98:99], 1.0 op_sel_hi:[1,0]
	v_pk_add_f32 v[100:101], v[100:101], 1.0 op_sel_hi:[1,0]
	v_pk_add_f32 v[102:103], v[102:103], 1.0 op_sel_hi:[1,0]
	v_rcp_f32_e32 v96, v96
	v_rcp_f32_e32 v97, v97
	v_rcp_f32_e32 v98, v98
	v_rcp_f32_e32 v99, v99
	v_rcp_f32_e32 v100, v100
	v_rcp_f32_e32 v101, v101
	v_rcp_f32_e32 v102, v102
	v_rcp_f32_e32 v103, v103
	v_pk_mul_f32 v[124:125], v[124:125], v[96:97]
	v_pk_mul_f32 v[126:127], v[126:127], v[98:99]
	v_pk_mul_f32 v[120:121], v[120:121], v[100:101]
	v_pk_mul_f32 v[122:123], v[122:123], v[102:103]
	v_cvt_pk_bf16_f32 v108, v140, v141
	v_cvt_pk_bf16_f32 v109, v142, v143
	v_cvt_pk_bf16_f32 v110, v136, v137
	v_cvt_pk_bf16_f32 v111, v138, v139
; __device__ __forceinline__ u32x4 pk8(f32x4 a, f32x4 b) { u32x4 w; w.x = pk2(a[0], a[1]); w.y = pk2(a[2], a[3]); w.z = pk2(b[0], b[1]); w.w = pk2(b[2], b[3]); return w; }
; __device__ __forceinline__ f32x4 silu4(f32x4 x) { f32x4 r; for (int i = 0; i < 4; ++i) r[i] = x[i] * sigm(x[i]); return r; }
; __device__ __forceinline__ float sigm(float x) { return __builtin_amdgcn_rcpf(1.f + __builtin_amdgcn_exp2f(-x * LOG2E)); }
;     __device__ __forceinline__ void operator()(const f32x4 (&acc)[2][2][4][2], const pg8::Unit& u, int wr, int wc, int fr_, int fq_) const {
;     ...
;                 } else if (pn < 5) {
;                     bf16_t* p = SGA + (size_t)row * 512 + (pn - 3) * 256 + cw;
;                     gst<u32x4>(p, pk8(silu4(a0), silu4(a1))); gst<u32x4>(p + 128, pk8(silu4(b0), silu4(b1)));
	global_store_dwordx4 v214, v[108:111], s[16:17]
	v_cvt_pk_bf16_f32 v222, v124, v125
	v_cvt_pk_bf16_f32 v223, v126, v127
	v_cvt_pk_bf16_f32 v224, v120, v121
	v_cvt_pk_bf16_f32 v225, v122, v123
	global_store_dwordx4 v214, v[222:225], s[16:17] offset:256
	s_add_u32 s16, s16, 0x4000
	s_addc_u32 s17, s17, 0
	v_pk_mul_f32 v[92:93], v[92:93], v[180:181] op_sel_hi:[1,0]
	v_pk_mul_f32 v[94:95], v[94:95], v[180:181] op_sel_hi:[1,0]
	v_pk_mul_f32 v[88:89], v[88:89], v[180:181] op_sel_hi:[1,0]
	v_pk_mul_f32 v[90:91], v[90:91], v[180:181] op_sel_hi:[1,0]
	v_pk_mul_f32 v[84:85], v[84:85], v[180:181] op_sel_hi:[1,0]
	v_pk_mul_f32 v[86:87], v[86:87], v[180:181] op_sel_hi:[1,0]
	v_pk_mul_f32 v[80:81], v[80:81], v[180:181] op_sel_hi:[1,0]
	v_pk_mul_f32 v[82:83], v[82:83], v[180:181] op_sel_hi:[1,0]
	v_pk_mul_f32 v[96:97], v[92:93], s[30:31]
	v_pk_mul_f32 v[98:99], v[94:95], s[30:31]
	v_pk_mul_f32 v[100:101], v[88:89], s[30:31]
	v_pk_mul_f32 v[102:103], v[90:91], s[30:31]
	v_exp_f32_e32 v96, v96
	v_exp_f32_e32 v97, v97
	v_exp_f32_e32 v98, v98
	v_exp_f32_e32 v99, v99
	v_exp_f32_e32 v100, v100
	v_exp_f32_e32 v101, v101
	v_exp_f32_e32 v102, v102
	v_exp_f32_e32 v103, v103
	v_pk_add_f32 v[96:97], v[96:97], 1.0 op_sel_hi:[1,0]
	v_pk_add_f32 v[98:99], v[98:99], 1.0 op_sel_hi:[1,0]
	v_pk_add_f32 v[100:101], v[100:101], 1.0 op_sel_hi:[1,0]
	v_pk_add_f32 v[102:103], v[102:103], 1.0 op_sel_hi:[1,0]
	v_rcp_f32_e32 v96, v96
	v_rcp_f32_e32 v97, v97
	v_rcp_f32_e32 v98, v98
	v_rcp_f32_e32 v99, v99
	v_rcp_f32_e32 v100, v100
	v_rcp_f32_e32 v101, v101
	v_rcp_f32_e32 v102, v102
	v_rcp_f32_e32 v103, v103
	v_pk_mul_f32 v[92:93], v[92:93], v[96:97]
	v_pk_mul_f32 v[94:95], v[94:95], v[98:99]
	v_pk_mul_f32 v[88:89], v[88:89], v[100:101]
	v_pk_mul_f32 v[90:91], v[90:91], v[102:103]
	v_pk_mul_f32 v[96:97], v[84:85], s[30:31]
	v_pk_mul_f32 v[98:99], v[86:87], s[30:31]
	v_pk_mul_f32 v[100:101], v[80:81], s[30:31]
	v_pk_mul_f32 v[102:103], v[82:83], s[30:31]
	v_exp_f32_e32 v96, v96
	v_exp_f32_e32 v97, v97
	v_exp_f32_e32 v98, v98
	v_exp_f32_e32 v99, v99
	v_exp_f32_e32 v100, v100
	v_exp_f32_e32 v101, v101
	v_exp_f32_e32 v102, v102
	v_exp_f32_e32 v103, v103
	v_pk_add_f32 v[96:97], v[96:97], 1.0 op_sel_hi:[1,0]
	v_pk_add_f32 v[98:99], v[98:99], 1.0 op_sel_hi:[1,0]
	v_pk_add_f32 v[100:101], v[100:101], 1.0 op_sel_hi:[1,0]
	v_pk_add_f32 v[102:103], v[102:103], 1.0 op_sel_hi:[1,0]
	v_rcp_f32_e32 v96, v96
	v_rcp_f32_e32 v97, v97
	v_rcp_f32_e32 v98, v98
	v_rcp_f32_e32 v99, v99
	v_rcp_f32_e32 v100, v100
	v_rcp_f32_e32 v101, v101
	v_rcp_f32_e32 v102, v102
	v_rcp_f32_e32 v103, v103
	v_pk_mul_f32 v[84:85], v[84:85], v[96:97]
	v_pk_mul_f32 v[86:87], v[86:87], v[98:99]
	v_pk_mul_f32 v[80:81], v[80:81], v[100:101]
	v_pk_mul_f32 v[82:83], v[82:83], v[102:103]
	v_cvt_pk_bf16_f32 v104, v92, v93
	v_cvt_pk_bf16_f32 v105, v94, v95
	v_cvt_pk_bf16_f32 v106, v88, v89
	v_cvt_pk_bf16_f32 v107, v90, v91
	global_store_dwordx4 v214, v[104:107], s[16:17]
	v_cvt_pk_bf16_f32 v218, v84, v85
	v_cvt_pk_bf16_f32 v219, v86, v87
	v_cvt_pk_bf16_f32 v220, v80, v81
	v_cvt_pk_bf16_f32 v221, v82, v83
	global_store_dwordx4 v214, v[218:221], s[16:17] offset:256
	s_add_u32 s16, s16, 0x4000
	s_addc_u32 s17, s17, 0
	v_pk_mul_f32 v[76:77], v[76:77], v[182:183] op_sel_hi:[1,0]
	v_pk_mul_f32 v[78:79], v[78:79], v[182:183] op_sel_hi:[1,0]
	v_pk_mul_f32 v[72:73], v[72:73], v[182:183] op_sel_hi:[1,0]
	v_pk_mul_f32 v[74:75], v[74:75], v[182:183] op_sel_hi:[1,0]
	v_pk_mul_f32 v[68:69], v[68:69], v[182:183] op_sel_hi:[1,0]
	v_pk_mul_f32 v[70:71], v[70:71], v[182:183] op_sel_hi:[1,0]
	v_pk_mul_f32 v[64:65], v[64:65], v[182:183] op_sel_hi:[1,0]
	v_pk_mul_f32 v[66:67], v[66:67], v[182:183] op_sel_hi:[1,0]
	v_pk_mul_f32 v[96:97], v[76:77], s[30:31]
	v_pk_mul_f32 v[98:99], v[78:79], s[30:31]
	v_pk_mul_f32 v[100:101], v[72:73], s[30:31]
	v_pk_mul_f32 v[102:103], v[74:75], s[30:31]
	v_exp_f32_e32 v96, v96
	v_exp_f32_e32 v97, v97
	v_exp_f32_e32 v98, v98
	v_exp_f32_e32 v99, v99
	v_exp_f32_e32 v100, v100
	v_exp_f32_e32 v101, v101
	v_exp_f32_e32 v102, v102
	v_exp_f32_e32 v103, v103
	v_pk_add_f32 v[96:97], v[96:97], 1.0 op_sel_hi:[1,0]
	v_pk_add_f32 v[98:99], v[98:99], 1.0 op_sel_hi:[1,0]
	v_pk_add_f32 v[100:101], v[100:101], 1.0 op_sel_hi:[1,0]
	v_pk_add_f32 v[102:103], v[102:103], 1.0 op_sel_hi:[1,0]
	v_rcp_f32_e32 v96, v96
	v_rcp_f32_e32 v97, v97
	v_rcp_f32_e32 v98, v98
	v_rcp_f32_e32 v99, v99
	v_rcp_f32_e32 v100, v100
	v_rcp_f32_e32 v101, v101
	v_rcp_f32_e32 v102, v102
	v_rcp_f32_e32 v103, v103
	v_pk_mul_f32 v[76:77], v[76:77], v[96:97]
	v_pk_mul_f32 v[78:79], v[78:79], v[98:99]
	v_pk_mul_f32 v[72:73], v[72:73], v[100:101]
	v_pk_mul_f32 v[74:75], v[74:75], v[102:103]
	v_pk_mul_f32 v[96:97], v[68:69], s[30:31]
	v_pk_mul_f32 v[98:99], v[70:71], s[30:31]
	v_pk_mul_f32 v[100:101], v[64:65], s[30:31]
	v_pk_mul_f32 v[102:103], v[66:67], s[30:31]
	v_exp_f32_e32 v96, v96
	v_exp_f32_e32 v97, v97
	v_exp_f32_e32 v98, v98
	v_exp_f32_e32 v99, v99
	v_exp_f32_e32 v100, v100
	v_exp_f32_e32 v101, v101
	v_exp_f32_e32 v102, v102
	v_exp_f32_e32 v103, v103
	v_pk_add_f32 v[96:97], v[96:97], 1.0 op_sel_hi:[1,0]
	v_pk_add_f32 v[98:99], v[98:99], 1.0 op_sel_hi:[1,0]
	v_pk_add_f32 v[100:101], v[100:101], 1.0 op_sel_hi:[1,0]
	v_pk_add_f32 v[102:103], v[102:103], 1.0 op_sel_hi:[1,0]
	v_rcp_f32_e32 v96, v96
	v_rcp_f32_e32 v97, v97
	v_rcp_f32_e32 v98, v98
	v_rcp_f32_e32 v99, v99
	v_rcp_f32_e32 v100, v100
	v_rcp_f32_e32 v101, v101
	v_rcp_f32_e32 v102, v102
	v_rcp_f32_e32 v103, v103
	v_pk_mul_f32 v[68:69], v[68:69], v[96:97]
	v_pk_mul_f32 v[70:71], v[70:71], v[98:99]
	v_pk_mul_f32 v[64:65], v[64:65], v[100:101]
	v_pk_mul_f32 v[66:67], v[66:67], v[102:103]
	v_cvt_pk_bf16_f32 v108, v76, v77
; __device__ __forceinline__ u32x4 pk8(f32x4 a, f32x4 b) { u32x4 w; w.x = pk2(a[0], a[1]); w.y = pk2(a[2], a[3]); w.z = pk2(b[0], b[1]); w.w = pk2(b[2], b[3]); return w; }
; __device__ __forceinline__ f32x4 silu4(f32x4 x) { f32x4 r; for (int i = 0; i < 4; ++i) r[i] = x[i] * sigm(x[i]); return r; }
; __device__ __forceinline__ float sigm(float x) { return __builtin_amdgcn_rcpf(1.f + __builtin_amdgcn_exp2f(-x * LOG2E)); }
;     __device__ __forceinline__ void operator()(const f32x4 (&acc)[2][2][4][2], const pg8::Unit& u, int wr, int wc, int fr_, int fq_) const {
;     ...
;                 } else if (pn < 5) {
;                     bf16_t* p = SGA + (size_t)row * 512 + (pn - 3) * 256 + cw;
;                     gst<u32x4>(p, pk8(silu4(a0), silu4(a1))); gst<u32x4>(p + 128, pk8(silu4(b0), silu4(b1)));
	v_cvt_pk_bf16_f32 v109, v78, v79
	v_cvt_pk_bf16_f32 v110, v72, v73
	v_cvt_pk_bf16_f32 v111, v74, v75
	global_store_dwordx4 v214, v[108:111], s[16:17]
	v_cvt_pk_bf16_f32 v222, v68, v69
	v_cvt_pk_bf16_f32 v223, v70, v71
	v_cvt_pk_bf16_f32 v224, v64, v65
	v_cvt_pk_bf16_f32 v225, v66, v67
	global_store_dwordx4 v214, v[222:225], s[16:17] offset:256
	s_add_u32 s16, s16, 0x14000
	s_addc_u32 s17, s17, 0
	v_pk_mul_f32 v[60:61], v[60:61], v[184:185] op_sel_hi:[1,0]
	v_pk_mul_f32 v[62:63], v[62:63], v[184:185] op_sel_hi:[1,0]
	v_pk_mul_f32 v[56:57], v[56:57], v[184:185] op_sel_hi:[1,0]
	v_pk_mul_f32 v[58:59], v[58:59], v[184:185] op_sel_hi:[1,0]
	v_pk_mul_f32 v[52:53], v[52:53], v[184:185] op_sel_hi:[1,0]
	v_pk_mul_f32 v[54:55], v[54:55], v[184:185] op_sel_hi:[1,0]
	v_pk_mul_f32 v[48:49], v[48:49], v[184:185] op_sel_hi:[1,0]
	v_pk_mul_f32 v[50:51], v[50:51], v[184:185] op_sel_hi:[1,0]
	v_pk_mul_f32 v[96:97], v[60:61], s[30:31]
	v_pk_mul_f32 v[98:99], v[62:63], s[30:31]
	v_pk_mul_f32 v[100:101], v[56:57], s[30:31]
	v_pk_mul_f32 v[102:103], v[58:59], s[30:31]
	v_exp_f32_e32 v96, v96
	v_exp_f32_e32 v97, v97
	v_exp_f32_e32 v98, v98
	v_exp_f32_e32 v99, v99
	v_exp_f32_e32 v100, v100
	v_exp_f32_e32 v101, v101
	v_exp_f32_e32 v102, v102
	v_exp_f32_e32 v103, v103
	v_pk_add_f32 v[96:97], v[96:97], 1.0 op_sel_hi:[1,0]
	v_pk_add_f32 v[98:99], v[98:99], 1.0 op_sel_hi:[1,0]
	v_pk_add_f32 v[100:101], v[100:101], 1.0 op_sel_hi:[1,0]
	v_pk_add_f32 v[102:103], v[102:103], 1.0 op_sel_hi:[1,0]
	v_rcp_f32_e32 v96, v96
	v_rcp_f32_e32 v97, v97
	v_rcp_f32_e32 v98, v98
	v_rcp_f32_e32 v99, v99
	v_rcp_f32_e32 v100, v100
	v_rcp_f32_e32 v101, v101
	v_rcp_f32_e32 v102, v102
	v_rcp_f32_e32 v103, v103
	v_pk_mul_f32 v[60:61], v[60:61], v[96:97]
	v_pk_mul_f32 v[62:63], v[62:63], v[98:99]
	v_pk_mul_f32 v[56:57], v[56:57], v[100:101]
	v_pk_mul_f32 v[58:59], v[58:59], v[102:103]
	v_pk_mul_f32 v[96:97], v[52:53], s[30:31]
	v_pk_mul_f32 v[98:99], v[54:55], s[30:31]
	v_pk_mul_f32 v[100:101], v[48:49], s[30:31]
	v_pk_mul_f32 v[102:103], v[50:51], s[30:31]
	v_exp_f32_e32 v96, v96
	v_exp_f32_e32 v97, v97
	v_exp_f32_e32 v98, v98
	v_exp_f32_e32 v99, v99
	v_exp_f32_e32 v100, v100
	v_exp_f32_e32 v101, v101
	v_exp_f32_e32 v102, v102
	v_exp_f32_e32 v103, v103
	v_pk_add_f32 v[96:97], v[96:97], 1.0 op_sel_hi:[1,0]
	v_pk_add_f32 v[98:99], v[98:99], 1.0 op_sel_hi:[1,0]
	v_pk_add_f32 v[100:101], v[100:101], 1.0 op_sel_hi:[1,0]
	v_pk_add_f32 v[102:103], v[102:103], 1.0 op_sel_hi:[1,0]
	v_rcp_f32_e32 v96, v96
	v_rcp_f32_e32 v97, v97
	v_rcp_f32_e32 v98, v98
	v_rcp_f32_e32 v99, v99
	v_rcp_f32_e32 v100, v100
	v_rcp_f32_e32 v101, v101
	v_rcp_f32_e32 v102, v102
	v_rcp_f32_e32 v103, v103
	v_pk_mul_f32 v[52:53], v[52:53], v[96:97]
	v_pk_mul_f32 v[54:55], v[54:55], v[98:99]
	v_pk_mul_f32 v[48:49], v[48:49], v[100:101]
	v_pk_mul_f32 v[50:51], v[50:51], v[102:103]
	v_cvt_pk_bf16_f32 v104, v60, v61
	v_cvt_pk_bf16_f32 v105, v62, v63
	v_cvt_pk_bf16_f32 v106, v56, v57
	v_cvt_pk_bf16_f32 v107, v58, v59
	global_store_dwordx4 v214, v[104:107], s[16:17]
	v_cvt_pk_bf16_f32 v218, v52, v53
	v_cvt_pk_bf16_f32 v219, v54, v55
	v_cvt_pk_bf16_f32 v220, v48, v49
	v_cvt_pk_bf16_f32 v221, v50, v51
	global_store_dwordx4 v214, v[218:221], s[16:17] offset:256
	s_add_u32 s16, s16, 0x4000
	s_addc_u32 s17, s17, 0
	v_pk_mul_f32 v[44:45], v[44:45], v[186:187] op_sel_hi:[1,0]
	v_pk_mul_f32 v[46:47], v[46:47], v[186:187] op_sel_hi:[1,0]
	v_pk_mul_f32 v[40:41], v[40:41], v[186:187] op_sel_hi:[1,0]
	v_pk_mul_f32 v[42:43], v[42:43], v[186:187] op_sel_hi:[1,0]
	v_pk_mul_f32 v[36:37], v[36:37], v[186:187] op_sel_hi:[1,0]
	v_pk_mul_f32 v[38:39], v[38:39], v[186:187] op_sel_hi:[1,0]
	v_pk_mul_f32 v[32:33], v[32:33], v[186:187] op_sel_hi:[1,0]
	v_pk_mul_f32 v[34:35], v[34:35], v[186:187] op_sel_hi:[1,0]
	v_pk_mul_f32 v[96:97], v[44:45], s[30:31]
	v_pk_mul_f32 v[98:99], v[46:47], s[30:31]
	v_pk_mul_f32 v[100:101], v[40:41], s[30:31]
	v_pk_mul_f32 v[102:103], v[42:43], s[30:31]
	v_exp_f32_e32 v96, v96
	v_exp_f32_e32 v97, v97
	v_exp_f32_e32 v98, v98
	v_exp_f32_e32 v99, v99
	v_exp_f32_e32 v100, v100
	v_exp_f32_e32 v101, v101
	v_exp_f32_e32 v102, v102
	v_exp_f32_e32 v103, v103
	v_pk_add_f32 v[96:97], v[96:97], 1.0 op_sel_hi:[1,0]
	v_pk_add_f32 v[98:99], v[98:99], 1.0 op_sel_hi:[1,0]
	v_pk_add_f32 v[100:101], v[100:101], 1.0 op_sel_hi:[1,0]
	v_pk_add_f32 v[102:103], v[102:103], 1.0 op_sel_hi:[1,0]
	v_rcp_f32_e32 v96, v96
	v_rcp_f32_e32 v97, v97
	v_rcp_f32_e32 v98, v98
	v_rcp_f32_e32 v99, v99
	v_rcp_f32_e32 v100, v100
	v_rcp_f32_e32 v101, v101
	v_rcp_f32_e32 v102, v102
	v_rcp_f32_e32 v103, v103
	v_pk_mul_f32 v[44:45], v[44:45], v[96:97]
	v_pk_mul_f32 v[46:47], v[46:47], v[98:99]
	v_pk_mul_f32 v[40:41], v[40:41], v[100:101]
	v_pk_mul_f32 v[42:43], v[42:43], v[102:103]
	v_pk_mul_f32 v[96:97], v[36:37], s[30:31]
	v_pk_mul_f32 v[98:99], v[38:39], s[30:31]
	v_pk_mul_f32 v[100:101], v[32:33], s[30:31]
	v_pk_mul_f32 v[102:103], v[34:35], s[30:31]
	v_exp_f32_e32 v96, v96
	v_exp_f32_e32 v97, v97
	v_exp_f32_e32 v98, v98
	v_exp_f32_e32 v99, v99
	v_exp_f32_e32 v100, v100
	v_exp_f32_e32 v101, v101
	v_exp_f32_e32 v102, v102
	v_exp_f32_e32 v103, v103
	v_pk_add_f32 v[96:97], v[96:97], 1.0 op_sel_hi:[1,0]
	v_pk_add_f32 v[98:99], v[98:99], 1.0 op_sel_hi:[1,0]
	v_pk_add_f32 v[100:101], v[100:101], 1.0 op_sel_hi:[1,0]
	v_pk_add_f32 v[102:103], v[102:103], 1.0 op_sel_hi:[1,0]
	v_rcp_f32_e32 v96, v96
	v_rcp_f32_e32 v97, v97
	v_rcp_f32_e32 v98, v98
	v_rcp_f32_e32 v99, v99
	v_rcp_f32_e32 v100, v100
	v_rcp_f32_e32 v101, v101
	v_rcp_f32_e32 v102, v102
	v_rcp_f32_e32 v103, v103
	v_pk_mul_f32 v[36:37], v[36:37], v[96:97]
	v_pk_mul_f32 v[38:39], v[38:39], v[98:99]
; __device__ __forceinline__ u32x4 pk8(f32x4 a, f32x4 b) { u32x4 w; w.x = pk2(a[0], a[1]); w.y = pk2(a[2], a[3]); w.z = pk2(b[0], b[1]); w.w = pk2(b[2], b[3]); return w; }
; __device__ __forceinline__ f32x4 silu4(f32x4 x) { f32x4 r; for (int i = 0; i < 4; ++i) r[i] = x[i] * sigm(x[i]); return r; }
; __device__ __forceinline__ float sigm(float x) { return __builtin_amdgcn_rcpf(1.f + __builtin_amdgcn_exp2f(-x * LOG2E)); }
;     __device__ __forceinline__ void operator()(const f32x4 (&acc)[2][2][4][2], const pg8::Unit& u, int wr, int wc, int fr_, int fq_) const {
;     ...
;                 } else if (pn < 5) {
;                     bf16_t* p = SGA + (size_t)row * 512 + (pn - 3) * 256 + cw;
;                     gst<u32x4>(p, pk8(silu4(a0), silu4(a1))); gst<u32x4>(p + 128, pk8(silu4(b0), silu4(b1)));
	v_pk_mul_f32 v[32:33], v[32:33], v[100:101]
	v_pk_mul_f32 v[34:35], v[34:35], v[102:103]
	v_cvt_pk_bf16_f32 v108, v44, v45
	v_cvt_pk_bf16_f32 v109, v46, v47
	v_cvt_pk_bf16_f32 v110, v40, v41
	v_cvt_pk_bf16_f32 v111, v42, v43
	global_store_dwordx4 v214, v[108:111], s[16:17]
	v_cvt_pk_bf16_f32 v222, v36, v37
	v_cvt_pk_bf16_f32 v223, v38, v39
	v_cvt_pk_bf16_f32 v224, v32, v33
	v_cvt_pk_bf16_f32 v225, v34, v35
	global_store_dwordx4 v214, v[222:225], s[16:17] offset:256
	s_add_u32 s16, s16, 0x4000
	s_addc_u32 s17, s17, 0
	v_pk_mul_f32 v[28:29], v[28:29], v[188:189] op_sel_hi:[1,0]
	v_pk_mul_f32 v[30:31], v[30:31], v[188:189] op_sel_hi:[1,0]
	v_pk_mul_f32 v[24:25], v[24:25], v[188:189] op_sel_hi:[1,0]
	v_pk_mul_f32 v[26:27], v[26:27], v[188:189] op_sel_hi:[1,0]
	v_pk_mul_f32 v[20:21], v[20:21], v[188:189] op_sel_hi:[1,0]
	v_pk_mul_f32 v[22:23], v[22:23], v[188:189] op_sel_hi:[1,0]
	v_pk_mul_f32 v[16:17], v[16:17], v[188:189] op_sel_hi:[1,0]
	v_pk_mul_f32 v[18:19], v[18:19], v[188:189] op_sel_hi:[1,0]
	v_pk_mul_f32 v[96:97], v[28:29], s[30:31]
	v_pk_mul_f32 v[98:99], v[30:31], s[30:31]
	v_pk_mul_f32 v[100:101], v[24:25], s[30:31]
	v_pk_mul_f32 v[102:103], v[26:27], s[30:31]
	v_exp_f32_e32 v96, v96
	v_exp_f32_e32 v97, v97
	v_exp_f32_e32 v98, v98
	v_exp_f32_e32 v99, v99
	v_exp_f32_e32 v100, v100
	v_exp_f32_e32 v101, v101
	v_exp_f32_e32 v102, v102
	v_exp_f32_e32 v103, v103
	v_pk_add_f32 v[96:97], v[96:97], 1.0 op_sel_hi:[1,0]
	v_pk_add_f32 v[98:99], v[98:99], 1.0 op_sel_hi:[1,0]
	v_pk_add_f32 v[100:101], v[100:101], 1.0 op_sel_hi:[1,0]
	v_pk_add_f32 v[102:103], v[102:103], 1.0 op_sel_hi:[1,0]
	v_rcp_f32_e32 v96, v96
	v_rcp_f32_e32 v97, v97
	v_rcp_f32_e32 v98, v98
	v_rcp_f32_e32 v99, v99
	v_rcp_f32_e32 v100, v100
	v_rcp_f32_e32 v101, v101
	v_rcp_f32_e32 v102, v102
	v_rcp_f32_e32 v103, v103
	v_pk_mul_f32 v[28:29], v[28:29], v[96:97]
	v_pk_mul_f32 v[30:31], v[30:31], v[98:99]
	v_pk_mul_f32 v[24:25], v[24:25], v[100:101]
	v_pk_mul_f32 v[26:27], v[26:27], v[102:103]
	v_pk_mul_f32 v[96:97], v[20:21], s[30:31]
	v_pk_mul_f32 v[98:99], v[22:23], s[30:31]
	v_pk_mul_f32 v[100:101], v[16:17], s[30:31]
	v_pk_mul_f32 v[102:103], v[18:19], s[30:31]
	v_exp_f32_e32 v96, v96
	v_exp_f32_e32 v97, v97
	v_exp_f32_e32 v98, v98
	v_exp_f32_e32 v99, v99
	v_exp_f32_e32 v100, v100
	v_exp_f32_e32 v101, v101
	v_exp_f32_e32 v102, v102
	v_exp_f32_e32 v103, v103
	v_pk_add_f32 v[96:97], v[96:97], 1.0 op_sel_hi:[1,0]
	v_pk_add_f32 v[98:99], v[98:99], 1.0 op_sel_hi:[1,0]
	v_pk_add_f32 v[100:101], v[100:101], 1.0 op_sel_hi:[1,0]
	v_pk_add_f32 v[102:103], v[102:103], 1.0 op_sel_hi:[1,0]
	v_rcp_f32_e32 v96, v96
	v_rcp_f32_e32 v97, v97
	v_rcp_f32_e32 v98, v98
	v_rcp_f32_e32 v99, v99
	v_rcp_f32_e32 v100, v100
	v_rcp_f32_e32 v101, v101
	v_rcp_f32_e32 v102, v102
	v_rcp_f32_e32 v103, v103
	v_pk_mul_f32 v[20:21], v[20:21], v[96:97]
	v_pk_mul_f32 v[22:23], v[22:23], v[98:99]
	v_pk_mul_f32 v[16:17], v[16:17], v[100:101]
	v_pk_mul_f32 v[18:19], v[18:19], v[102:103]
	v_cvt_pk_bf16_f32 v104, v28, v29
	v_cvt_pk_bf16_f32 v105, v30, v31
	v_cvt_pk_bf16_f32 v106, v24, v25
	v_cvt_pk_bf16_f32 v107, v26, v27
	global_store_dwordx4 v214, v[104:107], s[16:17]
	v_cvt_pk_bf16_f32 v218, v20, v21
	v_cvt_pk_bf16_f32 v219, v22, v23
	v_cvt_pk_bf16_f32 v220, v16, v17
	v_cvt_pk_bf16_f32 v221, v18, v19
	global_store_dwordx4 v214, v[218:221], s[16:17] offset:256
	s_add_u32 s16, s16, 0x4000
	s_addc_u32 s17, s17, 0
	v_pk_mul_f32 v[12:13], v[12:13], v[190:191] op_sel_hi:[1,0]
	v_pk_mul_f32 v[14:15], v[14:15], v[190:191] op_sel_hi:[1,0]
	v_pk_mul_f32 v[8:9], v[8:9], v[190:191] op_sel_hi:[1,0]
	v_pk_mul_f32 v[10:11], v[10:11], v[190:191] op_sel_hi:[1,0]
	v_pk_mul_f32 v[4:5], v[4:5], v[190:191] op_sel_hi:[1,0]
	v_pk_mul_f32 v[6:7], v[6:7], v[190:191] op_sel_hi:[1,0]
	v_pk_mul_f32 v[0:1], v[0:1], v[190:191] op_sel_hi:[1,0]
	v_pk_mul_f32 v[2:3], v[2:3], v[190:191] op_sel_hi:[1,0]
	v_pk_mul_f32 v[96:97], v[12:13], s[30:31]
	v_pk_mul_f32 v[98:99], v[14:15], s[30:31]
	v_pk_mul_f32 v[100:101], v[8:9], s[30:31]
	v_pk_mul_f32 v[102:103], v[10:11], s[30:31]
	v_exp_f32_e32 v96, v96
	v_exp_f32_e32 v97, v97
	v_exp_f32_e32 v98, v98
	v_exp_f32_e32 v99, v99
	v_exp_f32_e32 v100, v100
	v_exp_f32_e32 v101, v101
	v_exp_f32_e32 v102, v102
	v_exp_f32_e32 v103, v103
	v_pk_add_f32 v[96:97], v[96:97], 1.0 op_sel_hi:[1,0]
	v_pk_add_f32 v[98:99], v[98:99], 1.0 op_sel_hi:[1,0]
	v_pk_add_f32 v[100:101], v[100:101], 1.0 op_sel_hi:[1,0]
	v_pk_add_f32 v[102:103], v[102:103], 1.0 op_sel_hi:[1,0]
	v_rcp_f32_e32 v96, v96
	v_rcp_f32_e32 v97, v97
	v_rcp_f32_e32 v98, v98
	v_rcp_f32_e32 v99, v99
	v_rcp_f32_e32 v100, v100
	v_rcp_f32_e32 v101, v101
	v_rcp_f32_e32 v102, v102
	v_rcp_f32_e32 v103, v103
	v_pk_mul_f32 v[12:13], v[12:13], v[96:97]
	v_pk_mul_f32 v[14:15], v[14:15], v[98:99]
	v_pk_mul_f32 v[8:9], v[8:9], v[100:101]
	v_pk_mul_f32 v[10:11], v[10:11], v[102:103]
	v_pk_mul_f32 v[96:97], v[4:5], s[30:31]
	v_pk_mul_f32 v[98:99], v[6:7], s[30:31]
	v_pk_mul_f32 v[100:101], v[0:1], s[30:31]
	v_pk_mul_f32 v[102:103], v[2:3], s[30:31]
	v_exp_f32_e32 v96, v96
	v_exp_f32_e32 v97, v97
	v_exp_f32_e32 v98, v98
	v_exp_f32_e32 v99, v99
	v_exp_f32_e32 v100, v100
	v_exp_f32_e32 v101, v101
	v_exp_f32_e32 v102, v102
	v_exp_f32_e32 v103, v103
	v_pk_add_f32 v[96:97], v[96:97], 1.0 op_sel_hi:[1,0]
	v_pk_add_f32 v[98:99], v[98:99], 1.0 op_sel_hi:[1,0]
	v_pk_add_f32 v[100:101], v[100:101], 1.0 op_sel_hi:[1,0]
	v_pk_add_f32 v[102:103], v[102:103], 1.0 op_sel_hi:[1,0]
	v_rcp_f32_e32 v96, v96
	v_rcp_f32_e32 v97, v97
	v_rcp_f32_e32 v98, v98
	v_rcp_f32_e32 v99, v99
	v_rcp_f32_e32 v100, v100
	v_rcp_f32_e32 v101, v101
	v_rcp_f32_e32 v102, v102
	v_rcp_f32_e32 v103, v103
	v_pk_mul_f32 v[4:5], v[4:5], v[96:97]
	v_pk_mul_f32 v[6:7], v[6:7], v[98:99]
	v_pk_mul_f32 v[0:1], v[0:1], v[100:101]
	v_pk_mul_f32 v[2:3], v[2:3], v[102:103]
	v_cvt_pk_bf16_f32 v108, v12, v13
	v_cvt_pk_bf16_f32 v109, v14, v15
	v_cvt_pk_bf16_f32 v110, v8, v9
	v_cvt_pk_bf16_f32 v111, v10, v11
	global_store_dwordx4 v214, v[108:111], s[16:17]
	v_cvt_pk_bf16_f32 v222, v4, v5
	v_cvt_pk_bf16_f32 v223, v6, v7
	v_cvt_pk_bf16_f32 v224, v0, v1
	v_cvt_pk_bf16_f32 v225, v2, v3
	global_store_dwordx4 v214, v[222:225], s[16:17] offset:256
	s_branch .LBB0_580

; __device__ __forceinline__ unsigned xb_ld(unsigned* p)              { return __hip_atomic_load((GAS unsigned*)p, __ATOMIC_RELAXED, __HIP_MEMORY_SCOPE_AGENT); }
; __device__ __forceinline__ unsigned xb_add(unsigned* p, unsigned v) { return __hip_atomic_fetch_add((GAS unsigned*)p, v, __ATOMIC_RELAXED, __HIP_MEMORY_SCOPE_AGENT); }
; #define XB_SPIN(cond, bar) do { unsigned _sp = 0; while (cond) { __builtin_amdgcn_s_sleep(1); \
;     if ((++_sp & 255u) == 0u) { if (xb_ld(&(bar)[XB_TMO])) break; if (_sp > XB_SPIN_CAP) { atomicAdd(&(bar)[XB_TMO], 1u); break; } } } } while (0)
; __device__ __forceinline__ void xcd_barrier(const XcdBarrier& b) {
;     ...
;         const unsigned old = xb_add(&bar[XB_XSUB(bx)], 1u);
;         const unsigned gen = old / nloc;
;         if (old + 1u == (gen + 1u) * nloc) {
;             __builtin_amdgcn_fence(__ATOMIC_RELEASE, "agent");
;             asm volatile("s_waitcnt vmcnt(0)" ::: "memory");
;             const unsigned og = xb_add(&bar[XB_TOP], 1u);
;             const unsigned tg = og / nx;
;             if (og + 1u == (tg + 1u) * nx) xb_add(&bar[XB_TOPGEN], 1u);
;             else XB_SPIN(xb_ld(&bar[XB_TOPGEN]) == tg, bar);
;             __builtin_amdgcn_fence(__ATOMIC_ACQUIRE, "agent");
;             xb_add(&bar[XB_XGEN(bx)], 1u);
;             asm volatile("s_waitcnt vmcnt(0)" ::: "memory");
;         } else {
;             XB_SPIN(xb_ld(&bar[XB_XGEN(bx)]) == gen, bar);
;             __builtin_amdgcn_fence(__ATOMIC_ACQUIRE, "agent");
.LBB0_611:
	s_or_b64 exec, exec, s[10:11]
	v_cvt_f32_u32_e32 v4, v2
	s_waitcnt vmcnt(0)
	v_readfirstlane_b32 s8, v3
	v_sub_u32_e32 v3, 0, v2
	v_rcp_iflag_f32_e32 v4, v4
	v_add_u32_e32 v5, s8, v0
	v_mul_f32_e32 v4, 0x4f7ffffe, v4
	v_cvt_u32_f32_e32 v4, v4
	v_mul_lo_u32 v0, v3, v4
	v_mul_hi_u32 v0, v4, v0
	v_add_u32_e32 v0, v4, v0
	v_mul_hi_u32 v0, v5, v0
	v_mul_lo_u32 v3, v0, v2
	v_sub_u32_e32 v3, v5, v3
	v_add_u32_e32 v4, 1, v0
	v_cmp_ge_u32_e32 vcc, v3, v2
	s_nop 1
	v_cndmask_b32_e32 v0, v0, v4, vcc
	v_sub_u32_e32 v4, v3, v2
	v_cndmask_b32_e32 v3, v3, v4, vcc
	v_add_u32_e32 v4, 1, v0
	v_cmp_ge_u32_e32 vcc, v3, v2
	v_add_u32_e32 v3, 1, v5
	s_nop 0
	v_cndmask_b32_e32 v0, v0, v4, vcc
	v_mul_lo_u32 v4, v2, v0
	v_add_u32_e32 v2, v4, v2
	v_cmp_ne_u32_e32 vcc, v3, v2
	s_and_saveexec_b64 s[8:9], vcc
	s_xor_b64 s[8:9], exec, s[8:9]
	s_cbranch_execz .LBB0_624
	buffer_inv sc1
	s_add_i32 s20, s2, 0x900
	s_lshl_b64 s[10:11], s[20:21], 2
	s_add_u32 s12, s6, s10
	s_addc_u32 s13, s7, s11
	s_waitcnt lgkmcnt(0)
	global_load_dword v1, v193, s[12:13] sc1
	s_waitcnt vmcnt(0)
	v_cmp_eq_u32_e32 vcc, v1, v0
	s_and_saveexec_b64 s[10:11], vcc
	s_cbranch_execz .LBB0_623
	s_mov_b32 s20, 1
	s_mov_b64 s[14:15], 0
	s_branch .LBB0_615

; __device__ __forceinline__ unsigned xb_ld(unsigned* p)              { return __hip_atomic_load((GAS unsigned*)p, __ATOMIC_RELAXED, __HIP_MEMORY_SCOPE_AGENT); }
; __device__ __forceinline__ unsigned xb_add(unsigned* p, unsigned v) { return __hip_atomic_fetch_add((GAS unsigned*)p, v, __ATOMIC_RELAXED, __HIP_MEMORY_SCOPE_AGENT); }
; #define XB_SPIN(cond, bar) do { unsigned _sp = 0; while (cond) { __builtin_amdgcn_s_sleep(1); \
;     if ((++_sp & 255u) == 0u) { if (xb_ld(&(bar)[XB_TMO])) break; if (_sp > XB_SPIN_CAP) { atomicAdd(&(bar)[XB_TMO], 1u); break; } } } } while (0)
; __device__ __forceinline__ void xcd_barrier(const XcdBarrier& b) {
;     ...
;         const unsigned old = xb_add(&bar[XB_XSUB(bx)], 1u);
;         const unsigned gen = old / nloc;
;         if (old + 1u == (gen + 1u) * nloc) {
;             __builtin_amdgcn_fence(__ATOMIC_RELEASE, "agent");
;             asm volatile("s_waitcnt vmcnt(0)" ::: "memory");
;             const unsigned og = xb_add(&bar[XB_TOP], 1u);
;             const unsigned tg = og / nx;
;             if (og + 1u == (tg + 1u) * nx) xb_add(&bar[XB_TOPGEN], 1u);
;             else XB_SPIN(xb_ld(&bar[XB_TOPGEN]) == tg, bar);
;             __builtin_amdgcn_fence(__ATOMIC_ACQUIRE, "agent");
;             xb_add(&bar[XB_XGEN(bx)], 1u);
;             asm volatile("s_waitcnt vmcnt(0)" ::: "memory");
;         } else {
;             XB_SPIN(xb_ld(&bar[XB_XGEN(bx)]) == gen, bar);
;             __builtin_amdgcn_fence(__ATOMIC_ACQUIRE, "agent");
.LBB0_713:
	s_or_b64 exec, exec, s[12:13]
	v_cvt_f32_u32_e32 v4, v2
	s_waitcnt vmcnt(0)
	v_readfirstlane_b32 s3, v3
	v_sub_u32_e32 v3, 0, v2
	v_rcp_iflag_f32_e32 v4, v4
	v_add_u32_e32 v5, s3, v1
	v_mul_f32_e32 v4, 0x4f7ffffe, v4
	v_cvt_u32_f32_e32 v4, v4
	v_mul_lo_u32 v1, v3, v4
	v_mul_hi_u32 v1, v4, v1
	v_add_u32_e32 v1, v4, v1
	v_mul_hi_u32 v1, v5, v1
	v_mul_lo_u32 v3, v1, v2
	v_sub_u32_e32 v3, v5, v3
	v_add_u32_e32 v4, 1, v1
	v_cmp_ge_u32_e32 vcc, v3, v2
	s_nop 1
	v_cndmask_b32_e32 v1, v1, v4, vcc
	v_sub_u32_e32 v4, v3, v2
	v_cndmask_b32_e32 v3, v3, v4, vcc
	v_add_u32_e32 v4, 1, v1
	v_cmp_ge_u32_e32 vcc, v3, v2
	v_add_u32_e32 v3, 1, v5
	s_nop 0
	v_cndmask_b32_e32 v1, v1, v4, vcc
	v_mul_lo_u32 v4, v2, v1
	v_add_u32_e32 v2, v4, v2
	v_cmp_ne_u32_e32 vcc, v3, v2
	s_and_saveexec_b64 s[6:7], vcc
	s_xor_b64 s[10:11], exec, s[6:7]
	s_cbranch_execz .LBB0_726
	buffer_inv sc1
	s_add_i32 s20, s2, 0x900
	s_lshl_b64 s[6:7], s[20:21], 2
	s_add_u32 s14, s8, s6
	s_addc_u32 s15, s9, s7
	s_waitcnt lgkmcnt(0)
	global_load_dword v0, v193, s[14:15] sc1
	s_waitcnt vmcnt(0)
	v_cmp_eq_u32_e32 vcc, v0, v1
	s_and_saveexec_b64 s[12:13], vcc
	s_cbranch_execz .LBB0_725
	s_mov_b32 s3, 1
	s_mov_b64 s[16:17], 0
	s_branch .LBB0_717

; __device__ __forceinline__ unsigned xb_ld(unsigned* p)              { return __hip_atomic_load((GAS unsigned*)p, __ATOMIC_RELAXED, __HIP_MEMORY_SCOPE_AGENT); }
; #define XB_SPIN(cond, bar) do { unsigned _sp = 0; while (cond) { __builtin_amdgcn_s_sleep(1); \
;     if ((++_sp & 255u) == 0u) { if (xb_ld(&(bar)[XB_TMO])) break; if (_sp > XB_SPIN_CAP) { atomicAdd(&(bar)[XB_TMO], 1u); break; } } } } while (0)
; __device__ __forceinline__ void xcd_barrier(const XcdBarrier& b) {
;     ...
;             XB_SPIN(xb_ld(&bar[XB_XGEN(bx)]) == gen, bar);
;             __builtin_amdgcn_fence(__ATOMIC_ACQUIRE, "agent");
;             asm volatile("s_waitcnt vmcnt(0)" ::: "memory");
.LBB0_725:
	s_or_b64 exec, exec, s[12:13]
	s_waitcnt vmcnt(0) lgkmcnt(0)
	s_nop 0
	s_waitcnt vmcnt(0)

; __device__ __forceinline__ unsigned xb_ld(unsigned* p)              { return __hip_atomic_load((GAS unsigned*)p, __ATOMIC_RELAXED, __HIP_MEMORY_SCOPE_AGENT); }
; __device__ __forceinline__ unsigned xb_add(unsigned* p, unsigned v) { return __hip_atomic_fetch_add((GAS unsigned*)p, v, __ATOMIC_RELAXED, __HIP_MEMORY_SCOPE_AGENT); }
; #define XB_SPIN(cond, bar) do { unsigned _sp = 0; while (cond) { __builtin_amdgcn_s_sleep(1); \
;     if ((++_sp & 255u) == 0u) { if (xb_ld(&(bar)[XB_TMO])) break; if (_sp > XB_SPIN_CAP) { atomicAdd(&(bar)[XB_TMO], 1u); break; } } } } while (0)
; __device__ __forceinline__ void xcd_barrier(const XcdBarrier& b) {
;     ...
;         const unsigned old = xb_add(&bar[XB_XSUB(bx)], 1u);
;         const unsigned gen = old / nloc;
;         if (old + 1u == (gen + 1u) * nloc) {
;             __builtin_amdgcn_fence(__ATOMIC_RELEASE, "agent");
;             asm volatile("s_waitcnt vmcnt(0)" ::: "memory");
;             const unsigned og = xb_add(&bar[XB_TOP], 1u);
;             const unsigned tg = og / nx;
;             if (og + 1u == (tg + 1u) * nx) xb_add(&bar[XB_TOPGEN], 1u);
;             else XB_SPIN(xb_ld(&bar[XB_TOPGEN]) == tg, bar);
;             __builtin_amdgcn_fence(__ATOMIC_ACQUIRE, "agent");
;             xb_add(&bar[XB_XGEN(bx)], 1u);
;             asm volatile("s_waitcnt vmcnt(0)" ::: "memory");
;         } else {
;             XB_SPIN(xb_ld(&bar[XB_XGEN(bx)]) == gen, bar);
;             __builtin_amdgcn_fence(__ATOMIC_ACQUIRE, "agent");
.LBB0_794:
	s_or_b64 exec, exec, s[12:13]
	v_cvt_f32_u32_e32 v4, v2
	s_waitcnt vmcnt(0)
	v_readfirstlane_b32 s3, v3
	v_sub_u32_e32 v3, 0, v2
	v_rcp_iflag_f32_e32 v4, v4
	v_add_u32_e32 v5, s3, v1
	v_mul_f32_e32 v4, 0x4f7ffffe, v4
	v_cvt_u32_f32_e32 v4, v4
	v_mul_lo_u32 v1, v3, v4
	v_mul_hi_u32 v1, v4, v1
	v_add_u32_e32 v1, v4, v1
	v_mul_hi_u32 v1, v5, v1
	v_mul_lo_u32 v3, v1, v2
	v_sub_u32_e32 v3, v5, v3
	v_add_u32_e32 v4, 1, v1
	v_cmp_ge_u32_e32 vcc, v3, v2
	s_nop 1
	v_cndmask_b32_e32 v1, v1, v4, vcc
	v_sub_u32_e32 v4, v3, v2
	v_cndmask_b32_e32 v3, v3, v4, vcc
	v_add_u32_e32 v4, 1, v1
	v_cmp_ge_u32_e32 vcc, v3, v2
	v_add_u32_e32 v3, 1, v5
	s_nop 0
	v_cndmask_b32_e32 v1, v1, v4, vcc
	v_mul_lo_u32 v4, v2, v1
	v_add_u32_e32 v2, v4, v2
	v_cmp_ne_u32_e32 vcc, v3, v2
	s_and_saveexec_b64 s[10:11], vcc
	s_xor_b64 s[10:11], exec, s[10:11]
	s_cbranch_execz .LBB0_807
	buffer_inv sc1
	s_add_i32 s20, s2, 0x900
	s_lshl_b64 s[12:13], s[20:21], 2
	s_add_u32 s14, s8, s12
	s_addc_u32 s15, s9, s13
	s_waitcnt lgkmcnt(0)
	global_load_dword v0, v193, s[14:15] sc1
	s_waitcnt vmcnt(0)
	v_cmp_eq_u32_e32 vcc, v0, v1
	s_and_saveexec_b64 s[12:13], vcc
	s_cbranch_execz .LBB0_806
	s_mov_b32 s3, 1
	s_mov_b64 s[16:17], 0
	s_branch .LBB0_798

; __device__ __forceinline__ unsigned xb_ld(unsigned* p)              { return __hip_atomic_load((GAS unsigned*)p, __ATOMIC_RELAXED, __HIP_MEMORY_SCOPE_AGENT); }
; __device__ __forceinline__ unsigned xb_add(unsigned* p, unsigned v) { return __hip_atomic_fetch_add((GAS unsigned*)p, v, __ATOMIC_RELAXED, __HIP_MEMORY_SCOPE_AGENT); }
; #define XB_SPIN(cond, bar) do { unsigned _sp = 0; while (cond) { __builtin_amdgcn_s_sleep(1); \
;     if ((++_sp & 255u) == 0u) { if (xb_ld(&(bar)[XB_TMO])) break; if (_sp > XB_SPIN_CAP) { atomicAdd(&(bar)[XB_TMO], 1u); break; } } } } while (0)
; __device__ __forceinline__ void xcd_barrier(const XcdBarrier& b) {
;     ...
;         const unsigned old = xb_add(&bar[XB_XSUB(bx)], 1u);
;         const unsigned gen = old / nloc;
;         if (old + 1u == (gen + 1u) * nloc) {
;             __builtin_amdgcn_fence(__ATOMIC_RELEASE, "agent");
;             asm volatile("s_waitcnt vmcnt(0)" ::: "memory");
;             const unsigned og = xb_add(&bar[XB_TOP], 1u);
;             const unsigned tg = og / nx;
;             if (og + 1u == (tg + 1u) * nx) xb_add(&bar[XB_TOPGEN], 1u);
;             else XB_SPIN(xb_ld(&bar[XB_TOPGEN]) == tg, bar);
;             __builtin_amdgcn_fence(__ATOMIC_ACQUIRE, "agent");
;             xb_add(&bar[XB_XGEN(bx)], 1u);
;             asm volatile("s_waitcnt vmcnt(0)" ::: "memory");
;         } else {
;             XB_SPIN(xb_ld(&bar[XB_XGEN(bx)]) == gen, bar);
;             __builtin_amdgcn_fence(__ATOMIC_ACQUIRE, "agent");
.LBB0_893:
	s_or_b64 exec, exec, s[10:11]
	v_cvt_f32_u32_e32 v4, v2
	s_waitcnt vmcnt(0)
	v_readfirstlane_b32 s3, v3
	v_sub_u32_e32 v3, 0, v2
	v_rcp_iflag_f32_e32 v4, v4
	v_add_u32_e32 v5, s3, v1
	v_mul_f32_e32 v4, 0x4f7ffffe, v4
	v_cvt_u32_f32_e32 v4, v4
	v_mul_lo_u32 v1, v3, v4
	v_mul_hi_u32 v1, v4, v1
	v_add_u32_e32 v1, v4, v1
	v_mul_hi_u32 v1, v5, v1
	v_mul_lo_u32 v3, v1, v2
	v_sub_u32_e32 v3, v5, v3
	v_add_u32_e32 v4, 1, v1
	v_cmp_ge_u32_e32 vcc, v3, v2
	s_nop 1
	v_cndmask_b32_e32 v1, v1, v4, vcc
	v_sub_u32_e32 v4, v3, v2
	v_cndmask_b32_e32 v3, v3, v4, vcc
	v_add_u32_e32 v4, 1, v1
	v_cmp_ge_u32_e32 vcc, v3, v2
	v_add_u32_e32 v3, 1, v5
	s_nop 0
	v_cndmask_b32_e32 v1, v1, v4, vcc
	v_mul_lo_u32 v4, v2, v1
	v_add_u32_e32 v2, v4, v2
	v_cmp_ne_u32_e32 vcc, v3, v2
	s_and_saveexec_b64 s[8:9], vcc
	s_xor_b64 s[8:9], exec, s[8:9]
	s_cbranch_execz .LBB0_906
	buffer_inv sc1
	s_add_i32 s20, s2, 0x900
	s_lshl_b64 s[10:11], s[20:21], 2
	s_add_u32 s12, s6, s10
	s_addc_u32 s13, s7, s11
	s_waitcnt lgkmcnt(0)
	global_load_dword v0, v193, s[12:13] sc1
	s_waitcnt vmcnt(0)
	v_cmp_eq_u32_e32 vcc, v0, v1
	s_and_saveexec_b64 s[10:11], vcc
	s_cbranch_execz .LBB0_905
	s_mov_b32 s3, 1
	s_mov_b64 s[14:15], 0
	s_branch .LBB0_897
